# GEMM K-loop: LDS-DMA staging (global_load_lds) into swizzled LDS image, 16x16x32 MFMA, rss from A fragments only in wn==0 waves of use_rs GEMMs
# speedup vs baseline: 1.0718x; 1.0367x over previous
; DI int opaque_tid() { int t = threadIdx.x; asm volatile("" : "+v"(t)); return t; }
; DI void gemm_run(const GemmCfg c, char* smem, float* const g_h, u16* const g_hb, float* const g_out, const int final_out) {
;   const int tid = opaque_tid(), lane = tid & 63, w = __builtin_amdgcn_readfirstlane(tid >> 6), wm = w >> 1, wn = w & 1;
;   const int l31 = lane & 31, hh = lane >> 5;
;   float* s_rowss = (float*)(smem + 4 * GTS);
;   float* sW = (float*)(smem + w * (32 * 132 * 4));
;   const int tilesN = c.N >> 8;
;   const int K = c.K, nk = K >> 6;
;   const int G = gridDim.x;
;   const bool tail16 = (tilesN == 4) && (G == 256) && (c.epi == EPI_RESID || c.epi == EPI_PLAIN);
;   const int ntiles = (tail16 ? 64 : 65) * tilesN;
;   const int lrow = tid >> 3, lch = tid & 7;
;   const int Lb = ((G & 7) == 0) ? (int)(blockIdx.x & 7) * (G >> 3) + (int)(blockIdx.x >> 3) : (int)blockIdx.x;
;   const int srow = 8 * tilesN;
;   for (int slot = Lb; slot < ntiles; slot += G) {
;     const int sr = slot / srow, idx = slot - sr * srow;
;     const int tm = sr < 8 ? sr * 8 + (idx & 7) : 64;
;     const int tn = sr < 8 ? (idx >> 3) : idx;
;     const u16* Ag = c.A + (size_t)(tm * 256 + lrow) * c.lda + tn * c.a_koff_tn + lch * 8;
;     const u16* Bg = c.Bt + (size_t)(tn * 256 + lrow) * K + lch * 8;
;     const size_t astep = (size_t)64 * c.lda, bstep = (size_t)64 * K;
.LBB0_106:
	v_writelane_b32 v255, s14, 11
	v_readlane_b32 s6, v254, 46
	v_readlane_b32 s7, v254, 47
	v_writelane_b32 v255, s15, 12
	v_mov_b32_e32 v184, v210
	v_readlane_b32 s4, v255, 2
	s_cmp_eq_u32 s4, 3
	s_cselect_b64 s[4:5], -1, 0
	s_and_b64 s[4:5], s[6:7], s[4:5]
	v_writelane_b32 v255, s4, 13
	s_ashr_i32 s0, s0, 8
	v_readlane_b32 s12, v252, 23
	v_writelane_b32 v255, s5, 14
	v_readfirstlane_b32 s4, v184
	s_ashr_i32 s5, s4, 6
	s_cmp_eq_u32 s0, 4
	s_cselect_b64 s[6:7], -1, 0
	v_readlane_b32 s13, v252, 24
	s_and_b64 s[6:7], s[12:13], s[6:7]
	s_cmp_eq_u32 s52, 1
	s_cselect_b64 s[16:17], -1, 0
	s_cmp_lg_u32 s52, 1
	v_writelane_b32 v255, s5, 15
	s_cselect_b64 s[14:15], -1, 0
	v_writelane_b32 v255, s14, 16
	s_cmp_eq_u32 s52, 6
	v_readlane_b32 s12, v254, 28
	v_writelane_b32 v255, s15, 17
	s_cselect_b64 s[14:15], -1, 0
	v_writelane_b32 v255, s16, 18
	s_or_b64 s[14:15], s[16:17], s[14:15]
	s_and_b64 s[6:7], s[6:7], s[14:15]
	v_writelane_b32 v255, s17, 19
	v_writelane_b32 v255, s6, 20
	v_readlane_b32 s5, v254, 20
	v_readlane_b32 s13, v254, 29
	v_writelane_b32 v255, s7, 21
	s_and_b64 s[6:7], s[6:7], exec
	s_cselect_b32 s74, 64, 0x41
	s_mul_i32 s74, s74, s0
	s_cmp_ge_i32 s5, s74
	v_and_b32_e32 v185, 63, v184
	s_cbranch_scc1 .LBB0_433
	v_readlane_b32 s5, v255, 15
	s_ashr_i32 s63, s62, 31
	s_ashr_i32 s61, s60, 31
	s_and_b32 s75, s5, 1
	s_lshl_b32 s65, s0, 3
	v_and_b32_e32 v1, 7, v184
	s_ashr_i32 s68, s60, 6
	v_readlane_b32 s6, v255, 5
	s_lshl_b64 s[80:81], s[62:63], 6
	s_lshl_b64 s[82:83], s[60:61], 6
	s_waitcnt vmcnt(19)
	v_cvt_f32_i32_e32 v10, s60
	v_lshlrev_b32_e32 v166, 4, v1
	v_mov_b32_e32 v167, v165
	v_readlane_b32 s7, v255, 6
	s_cmp_gt_i32 s68, 3
	s_cselect_b64 s[16:17], -1, 0
	v_lshl_add_u64 v[168:169], s[6:7], 0, v[166:167]
	s_ashr_i32 s6, s4, 1
	v_and_b32_e32 v2, 31, v184
	s_and_b32 s86, s6, 0xffffffc0
	s_lshl_b32 s4, s75, 7
	v_lshlrev_b32_e32 v9, 2, v185
	s_mul_i32 s53, s5, 0x4200
	v_or_b32_e32 v4, s86, v2
	v_writelane_b32 v255, s4, 22
	v_or_b32_e32 v2, s4, v2
	v_xor_b32_e32 v187, 4, v9
	v_xor_b32_e32 v188, 8, v9
	v_xor_b32_e32 v189, 16, v9
	v_div_scale_f32 v9, s[4:5], v10, v10, 1.0
	v_rcp_f32_e32 v11, v9
	v_ashrrev_i32_e32 v186, 3, v184
	v_lshlrev_b32_e32 v0, 3, v1
	v_cmp_eq_u32_e64 s[40:41], 0, v1
	v_mov_b32_e32 v1, 0x24000
	v_lshl_add_u32 v190, v186, 2, v1
	v_fma_f32 v1, -v9, v11, 1.0
	s_cmp_lg_u32 s1, 0
	v_fmac_f32_e32 v11, v1, v11
	v_div_scale_f32 v1, vcc, 1.0, v10, 1.0
	s_cselect_b64 s[88:89], -1, 0
	s_ashr_i32 s87, s86, 31
	s_waitcnt vmcnt(18)
	v_mul_f32_e32 v12, v1, v11
	v_fma_f32 v13, -v9, v12, v1
	s_cmpk_eq_i32 s60, 0xb00
	v_fmac_f32_e32 v12, v13, v11
	s_cselect_b64 s[4:5], -1, 0
	s_ashr_i32 s63, s0, 31
	v_fma_f32 v1, -v9, v12, v1
	s_add_i32 s0, s65, s63
	v_div_fmas_f32 v1, v1, v11, v12
	s_xor_b32 s30, s0, s63
	v_div_fixup_f32 v191, v1, v10, 1.0
	v_cvt_f32_u32_e32 v1, s30
	v_readlane_b32 s0, v255, 11
	v_cndmask_b32_e64 v170, 1.0, 0.5, s[4:5]
	v_readlane_b32 s1, v255, 12
	v_rcp_iflag_f32_e32 v1, v1
	s_mov_b32 s4, s0
	s_ashr_i32 s5, s0, 31
	s_movk_i32 s0, 0x90
	v_mul_f32_e32 v1, 0x4f7ffffe, v1
	v_cvt_u32_f32_e32 v1, v1
	v_mul_lo_u32 v9, v186, s0
	v_mul_lo_u32 v4, v4, s0
	s_sub_i32 s0, 0, s30
	v_readfirstlane_b32 s1, v1
	s_mul_i32 s0, s0, s1
	s_mul_hi_u32 s0, s1, s0
	s_add_i32 s68, s68, -5
	s_add_i32 s69, s1, s0
	s_lshl_b64 s[90:91], s[60:61], 1
	s_mul_i32 s1, s86, 0x1600
	s_mul_hi_i32 s0, s86, 0x1600
	s_add_u32 s1, s56, s1
	v_writelane_b32 v255, s1, 23
	s_addc_u32 s0, s57, s0
	v_writelane_b32 v255, s0, 24
	s_lshl_b32 s0, s75, 6
	v_writelane_b32 v255, s0, 25
	s_lshl_b32 s0, s6, 2
	s_and_b32 s61, s0, 0xffffff00
	s_or_b32 s0, s86, 2
	v_writelane_b32 v255, s0, 26
	s_mov_b32 s0, s87
	v_writelane_b32 v255, s0, 27
	s_mov_b32 s0, s4
	s_lshl_b64 s[92:93], s[4:5], 1
	v_writelane_b32 v255, s0, 11
	s_lshl_b64 s[94:95], s[4:5], 3
	v_lshrrev_b32_e32 v5, 1, v184
	v_writelane_b32 v255, s1, 12
	s_add_u32 s0, s8, 0xffffff00
	s_addc_u32 s1, s9, -1
	v_writelane_b32 v255, s0, 28
	v_and_b32_e32 v5, 16, v5
	v_or_b32_e32 v3, 0x12000, v166
	v_writelane_b32 v255, s1, 29
	s_add_u32 s0, s56, 0x4000
	v_writelane_b32 v255, s0, 30
	s_addc_u32 s0, s57, 0
	v_writelane_b32 v255, s0, 31
	s_add_u32 s0, s76, 0xfffffc00
	s_addc_u32 s1, s77, -1
	v_writelane_b32 v255, s0, 32
	v_or_b32_e32 v6, 0x12000, v5
	v_or_b32_e32 v7, 0x1b000, v166
	v_writelane_b32 v255, s1, 33
	s_or_b32 s0, s86, 34
	v_writelane_b32 v255, s0, 34
	s_mov_b32 s0, s87
	v_writelane_b32 v255, s0, 35
	s_add_u32 s0, s76, 0x8400
	s_addc_u32 s1, s77, 0
	v_writelane_b32 v255, s0, 36
	v_or_b32_e32 v8, 0x1b000, v5
	v_mul_u32_u24_e32 v2, 0x90, v2
	v_writelane_b32 v255, s1, 37
	s_add_u32 s0, s8, 0x340
	s_addc_u32 s1, s9, 0
	v_writelane_b32 v255, s0, 38
	v_mov_b32_e32 v172, v170
	v_mov_b32_e32 v173, v170
	v_writelane_b32 v255, s1, 39
	s_or_b32 s0, s86, 32
	v_writelane_b32 v255, s0, 40
	s_mov_b32 s0, s87
	v_writelane_b32 v255, s0, 41
	v_writelane_b32 v255, s20, 42
	v_writelane_b32 v255, s16, 43
	v_lshlrev_b32_e32 v174, 1, v0
	v_and_b32_e32 v2, 15, v185
	v_lshrrev_b32_e32 v3, 4, v185
	v_and_b32_e32 v4, 7, v2
	v_xor_b32_e32 v3, v3, v4
	v_lshlrev_b32_e32 v3, 4, v3
	v_or_b32_e32 v4, s86, v2
	v_lshl_add_u32 v194, v4, 7, v3
	v_xor_b32_e32 v215, 64, v194
	v_mov_b32_e32 v4, s75
	v_lshl_or_b32 v4, v4, 7, v2
	v_lshl_add_u32 v195, v4, 7, v3
	v_add_u32_e32 v195, 0x12000, v195
	v_xor_b32_e32 v197, 64, v195
	v_mov_b32_e32 v175, v165
	v_readlane_b32 s48, v254, 20
	v_writelane_b32 v255, s17, 44
	s_branch .LBB0_110

; DI void lds_barrier() { asm volatile("s_waitcnt lgkmcnt(0)\n\ts_barrier" ::: "memory"); }
; #define G_LOAD(RA, RB, KT) { size_t as_ = astep, bs_ = bstep; asm volatile("" : "+s"(as_), "+s"(bs_)); \
;       _Pragma("unroll") for (int i = 0; i < 4; ++i) { RA[i] = *(const u32x4*)(Ag + i * as_ + (KT) * 64); RB[i] = *(const u32x4*)(Bg + i * bs_ + (KT) * 64); } }
; DI void gemm_run(const GemmCfg c, char* smem, float* const g_h, u16* const g_hb, float* const g_out, const int final_out) {
;     ...
;   for (int slot = Lb; slot < ntiles; slot += G) {
;     const int sr = slot / srow, idx = slot - sr * srow;
;     const int tm = sr < 8 ? sr * 8 + (idx & 7) : 64;
;     const int tn = sr < 8 ? (idx >> 3) : idx;
;     const u16* Ag = c.A + (size_t)(tm * 256 + lrow) * c.lda + tn * c.a_koff_tn + lch * 8;
;     const u16* Bg = c.Bt + (size_t)(tn * 256 + lrow) * K + lch * 8;
;     const size_t astep = (size_t)64 * c.lda, bstep = (size_t)64 * K;
;     f32x16 acc[2][4];
; #pragma unroll
;     for (int a = 0; a < 2; ++a)
; #pragma unroll
;       for (int b = 0; b < 4; ++b)
; #pragma unroll
;         for (int i = 0; i < 16; ++i) acc[a][b][i] = 0.f;
;     float ss[4] = {0.f, 0.f, 0.f, 0.f};
;     u32x4 ra0[4], rb0[4];
;     ...
;     G_LOAD(ra0, rb0, 0);
;     __syncthreads();
;     G_STORE(ra0, rb0, 0);
;     G_LOAD(ra0, rb0, 1);
;     lds_barrier();
;     int kt = 0;
.LBB0_110:
	s_abs_i32 s1, s48
	s_mul_hi_u32 s4, s1, s69
	s_mul_i32 s5, s4, s30
	s_ashr_i32 s0, s48, 31
	s_sub_i32 s1, s1, s5
	s_xor_b32 s0, s0, s63
	s_add_i32 s5, s4, 1
	s_sub_i32 s6, s1, s30
	s_cmp_ge_u32 s1, s30
	s_cselect_b32 s4, s5, s4
	s_cselect_b32 s1, s6, s1
	s_add_i32 s5, s4, 1
	s_cmp_ge_u32 s1, s30
	s_cselect_b32 s1, s5, s4
	s_xor_b32 s1, s1, s0
	s_sub_i32 s0, s1, s0
	s_mul_i32 s1, s0, s65
	s_sub_i32 s1, s48, s1
	s_lshl_b32 s4, s0, 3
	s_and_b32 s5, s48, 7
	s_or_b32 s4, s4, s5
	s_ashr_i32 s5, s1, 3
	s_cmp_lt_i32 s0, 8
	s_cselect_b32 s78, s4, 64
	s_waitcnt lgkmcnt(0)
	s_cselect_b32 s49, s5, s1
	v_lshrrev_b32_e32 v128, 3, v185
	v_and_b32_e32 v129, 7, v185
	v_xor_b32_e32 v129, v129, v128
	v_lshlrev_b32_e32 v129, 4, v129
	s_lshl_b32 s0, s62, 1
	v_mul_lo_u32 v130, v128, s0
	s_lshl_b32 s1, s62, 4
	v_add_u32_e32 v130, v130, v129
	v_add_u32_e32 v131, s1, v130
	v_add_u32_e32 v132, s1, v131
	v_add_u32_e32 v133, s1, v132
	s_lshl_b32 s0, s60, 1
	v_mul_lo_u32 v134, v128, s0
	s_lshl_b32 s1, s60, 4
	v_add_u32_e32 v134, v134, v129
	v_add_u32_e32 v135, s1, v134
	v_add_u32_e32 v136, s1, v135
	v_add_u32_e32 v137, s1, v136
	s_lshl_b32 s8, s75, 5
	s_add_i32 s8, s8, s86
	s_lshl_b32 s0, s78, 8
	s_add_i32 s0, s0, s8
	s_mul_i32 s0, s0, s62
	s_mul_i32 s1, s49, s2
	s_add_i32 s0, s0, s1
	s_lshl_b32 s0, s0, 1
	s_add_u32 s4, s54, s0
	s_addc_u32 s5, s55, 0
	v_readlane_b32 s6, v255, 5
	v_readlane_b32 s7, v255, 6
	s_lshl_b32 s0, s49, 8
	s_add_i32 s0, s0, s8
	s_mul_i32 s0, s0, s60
	s_lshl_b32 s0, s0, 1
	s_add_u32 s6, s6, s0
	s_addc_u32 s7, s7, 0
	s_lshl_b32 s8, s8, 7
	s_cmp_eq_u32 s75, 0
	s_cselect_b32 s9, 1, 0
	s_and_b32 s9, s9, s88
	s_barrier
	s_add_u32 m0, s8, 0x0
	s_nop 0
	global_load_lds_dwordx4 v130, s[4:5]
	s_add_u32 m0, s8, 0x12000
	s_nop 0
	global_load_lds_dwordx4 v134, s[6:7]
	s_add_u32 m0, s8, 0x400
	s_nop 0
	global_load_lds_dwordx4 v131, s[4:5]
	s_add_u32 m0, s8, 0x12400
	s_nop 0
	global_load_lds_dwordx4 v135, s[6:7]
	s_add_u32 m0, s8, 0x800
	s_nop 0
	global_load_lds_dwordx4 v132, s[4:5]
	s_add_u32 m0, s8, 0x12800
	s_nop 0
	global_load_lds_dwordx4 v136, s[6:7]
	s_add_u32 m0, s8, 0xc00
	s_nop 0
	global_load_lds_dwordx4 v133, s[4:5]
	s_add_u32 m0, s8, 0x12c00
	s_nop 0
	global_load_lds_dwordx4 v137, s[6:7]
	s_add_u32 s4, s4, 0x80
	s_addc_u32 s5, s5, 0
	s_add_u32 s6, s6, 0x80
	s_addc_u32 s7, s7, 0
	s_add_u32 m0, s8, 0x9000
	s_nop 0
	global_load_lds_dwordx4 v130, s[4:5]
	s_add_u32 m0, s8, 0x1b000
	s_nop 0
	global_load_lds_dwordx4 v134, s[6:7]
	s_add_u32 m0, s8, 0x9400
	s_nop 0
	global_load_lds_dwordx4 v131, s[4:5]
	s_add_u32 m0, s8, 0x1b400
	s_nop 0
	global_load_lds_dwordx4 v135, s[6:7]
	s_add_u32 m0, s8, 0x9800
	s_nop 0
	global_load_lds_dwordx4 v132, s[4:5]
	s_add_u32 m0, s8, 0x1b800
	s_nop 0
	global_load_lds_dwordx4 v136, s[6:7]
	s_add_u32 m0, s8, 0x9c00
	s_nop 0
	global_load_lds_dwordx4 v133, s[4:5]
	s_add_u32 m0, s8, 0x1bc00
	s_nop 0
	global_load_lds_dwordx4 v137, s[6:7]
	s_add_u32 s4, s4, 0x80
	s_addc_u32 s5, s5, 0
	s_add_u32 s6, s6, 0x80
	s_addc_u32 s7, s7, 0
	v_mov_b32_e32 v0, 0
	v_mov_b32_e32 v1, 0
	v_mov_b32_e32 v2, 0
	v_mov_b32_e32 v3, 0
	v_mov_b32_e32 v4, 0
	v_mov_b32_e32 v5, 0
	v_mov_b32_e32 v6, 0
	v_mov_b32_e32 v7, 0
	v_mov_b32_e32 v8, 0
	v_mov_b32_e32 v9, 0
	v_mov_b32_e32 v10, 0
	v_mov_b32_e32 v11, 0
	v_mov_b32_e32 v12, 0
	v_mov_b32_e32 v13, 0
	v_mov_b32_e32 v14, 0
	v_mov_b32_e32 v15, 0
	v_mov_b32_e32 v16, 0
	v_mov_b32_e32 v17, 0
	v_mov_b32_e32 v18, 0
	v_mov_b32_e32 v19, 0
	v_mov_b32_e32 v20, 0
	v_mov_b32_e32 v21, 0
	v_mov_b32_e32 v22, 0
	v_mov_b32_e32 v23, 0
	v_mov_b32_e32 v24, 0
	v_mov_b32_e32 v25, 0
	v_mov_b32_e32 v26, 0
	v_mov_b32_e32 v27, 0
	v_mov_b32_e32 v28, 0
	v_mov_b32_e32 v29, 0
	v_mov_b32_e32 v30, 0
	v_mov_b32_e32 v31, 0
	v_mov_b32_e32 v32, 0
	v_mov_b32_e32 v33, 0
	v_mov_b32_e32 v34, 0
	v_mov_b32_e32 v35, 0
	v_mov_b32_e32 v36, 0
	v_mov_b32_e32 v37, 0
	v_mov_b32_e32 v38, 0
	v_mov_b32_e32 v39, 0
	v_mov_b32_e32 v40, 0
	v_mov_b32_e32 v41, 0
	v_mov_b32_e32 v42, 0
	v_mov_b32_e32 v43, 0
	v_mov_b32_e32 v44, 0
	v_mov_b32_e32 v45, 0
	v_mov_b32_e32 v46, 0
	v_mov_b32_e32 v47, 0
	v_mov_b32_e32 v48, 0
	v_mov_b32_e32 v49, 0
	v_mov_b32_e32 v50, 0
	v_mov_b32_e32 v51, 0
	v_mov_b32_e32 v52, 0
	v_mov_b32_e32 v53, 0
	v_mov_b32_e32 v54, 0
	v_mov_b32_e32 v55, 0
	v_mov_b32_e32 v56, 0
	v_mov_b32_e32 v57, 0
	v_mov_b32_e32 v58, 0
	v_mov_b32_e32 v59, 0
	v_mov_b32_e32 v60, 0
	v_mov_b32_e32 v61, 0
	v_mov_b32_e32 v62, 0
	v_mov_b32_e32 v63, 0
	v_mov_b32_e32 v64, 0
	v_mov_b32_e32 v65, 0
	v_mov_b32_e32 v66, 0
	v_mov_b32_e32 v67, 0
	v_mov_b32_e32 v68, 0
	v_mov_b32_e32 v69, 0
	v_mov_b32_e32 v70, 0
	v_mov_b32_e32 v71, 0
	v_mov_b32_e32 v72, 0
	v_mov_b32_e32 v73, 0
	v_mov_b32_e32 v74, 0
	v_mov_b32_e32 v75, 0
	v_mov_b32_e32 v76, 0
	v_mov_b32_e32 v77, 0
	v_mov_b32_e32 v78, 0
	v_mov_b32_e32 v79, 0
	v_mov_b32_e32 v80, 0
	v_mov_b32_e32 v81, 0
	v_mov_b32_e32 v82, 0
	v_mov_b32_e32 v83, 0
	v_mov_b32_e32 v84, 0
	v_mov_b32_e32 v85, 0
	v_mov_b32_e32 v86, 0
	v_mov_b32_e32 v87, 0
	v_mov_b32_e32 v88, 0
	v_mov_b32_e32 v89, 0
	v_mov_b32_e32 v90, 0
	v_mov_b32_e32 v91, 0
	v_mov_b32_e32 v92, 0
	v_mov_b32_e32 v93, 0
	v_mov_b32_e32 v94, 0
	v_mov_b32_e32 v95, 0
	v_mov_b32_e32 v96, 0
	v_mov_b32_e32 v97, 0
	v_mov_b32_e32 v98, 0
	v_mov_b32_e32 v99, 0
	v_mov_b32_e32 v100, 0
	v_mov_b32_e32 v101, 0
	v_mov_b32_e32 v102, 0
	v_mov_b32_e32 v103, 0
	v_mov_b32_e32 v104, 0
	v_mov_b32_e32 v105, 0
	v_mov_b32_e32 v106, 0
	v_mov_b32_e32 v107, 0
	v_mov_b32_e32 v108, 0
	v_mov_b32_e32 v109, 0
	v_mov_b32_e32 v110, 0
	v_mov_b32_e32 v111, 0
	v_mov_b32_e32 v112, 0
	v_mov_b32_e32 v113, 0
	v_mov_b32_e32 v114, 0
	v_mov_b32_e32 v115, 0
	v_mov_b32_e32 v116, 0
	v_mov_b32_e32 v117, 0
	v_mov_b32_e32 v118, 0
	v_mov_b32_e32 v119, 0
	v_mov_b32_e32 v120, 0
	v_mov_b32_e32 v121, 0
	v_mov_b32_e32 v122, 0
	v_mov_b32_e32 v123, 0
	v_mov_b32_e32 v124, 0
	v_mov_b32_e32 v125, 0
	v_mov_b32_e32 v126, 0
	v_mov_b32_e32 v127, 0
	v_mov_b32_e32 v199, 0
	v_mov_b32_e32 v198, 0
	v_mov_b32_e32 v171, 0
	v_mov_b32_e32 v164, 0
	s_mov_b32 s1, 0
	s_add_i32 s0, s68, 3
	s_waitcnt vmcnt(8)
	s_barrier
	ds_read_b128 v[160:163], v194
	ds_read_b128 v[176:179], v194 offset:2048
	ds_read_b128 v[180:183], v194 offset:4096
	ds_read_b128 v[204:207], v195
	ds_read_b128 v[222:225], v195 offset:2048
	ds_read_b128 v[226:229], v195 offset:4096
	ds_read_b128 v[230:233], v195 offset:6144
	ds_read_b128 v[234:237], v195 offset:8192
	ds_read_b128 v[238:241], v195 offset:10240
	ds_read_b128 v[242:245], v195 offset:12288
	ds_read_b128 v[246:249], v195 offset:14336
	ds_read_b128 v[200:203], v194 offset:6144
	s_cmp_lg_u32 s9, 0
	s_cbranch_scc0 .Lgemm_kloop_n
; DI void lds_barrier() { asm volatile("s_waitcnt lgkmcnt(0)\n\ts_barrier" ::: "memory"); }
; #define G_LOAD(RA, RB, KT) { size_t as_ = astep, bs_ = bstep; asm volatile("" : "+s"(as_), "+s"(bs_)); \
;       _Pragma("unroll") for (int i = 0; i < 4; ++i) { RA[i] = *(const u32x4*)(Ag + i * as_ + (KT) * 64); RB[i] = *(const u32x4*)(Bg + i * bs_ + (KT) * 64); } }
; DI void gemm_run(const GemmCfg c, char* smem, float* const g_h, u16* const g_hb, float* const g_out, const int final_out) {
;     ...
;     G_LOAD(ra0, rb0, 0);
;     __syncthreads();
;     G_STORE(ra0, rb0, 0);
;     G_LOAD(ra0, rb0, 1);
;     lds_barrier();
;     int kt = 0;
;     for (; kt + 3 < nk; kt += 2) {
;       K_STEP(0, 1, kt + 2, true, true);
;       lds_barrier();
;       K_STEP(1, 0, kt + 3, true, true);
;       lds_barrier();
.LBB0_112:
	s_waitcnt lgkmcnt(8)
	v_mfma_f32_16x16x32_bf16 v[64:67], v[160:163], v[204:207], v[64:67]
	s_waitcnt lgkmcnt(7)
	v_mfma_f32_16x16x32_bf16 v[68:71], v[160:163], v[222:225], v[68:71]
	v_dot2c_f32_bf16_e32 v199, v160, v160
	v_dot2c_f32_bf16_e32 v199, v161, v161
	s_waitcnt lgkmcnt(6)
	v_mfma_f32_16x16x32_bf16 v[72:75], v[160:163], v[226:229], v[72:75]
	s_waitcnt lgkmcnt(5)
	v_mfma_f32_16x16x32_bf16 v[76:79], v[160:163], v[230:233], v[76:79]
	v_dot2c_f32_bf16_e32 v199, v162, v162
	v_dot2c_f32_bf16_e32 v199, v163, v163
	s_waitcnt lgkmcnt(4)
	v_mfma_f32_16x16x32_bf16 v[80:83], v[160:163], v[234:237], v[80:83]
	s_waitcnt lgkmcnt(3)
	v_mfma_f32_16x16x32_bf16 v[84:87], v[160:163], v[238:241], v[84:87]
	s_waitcnt lgkmcnt(2)
	v_mfma_f32_16x16x32_bf16 v[88:91], v[160:163], v[242:245], v[88:91]
	s_waitcnt lgkmcnt(1)
	v_mfma_f32_16x16x32_bf16 v[92:95], v[160:163], v[246:249], v[92:95]
	ds_read_b128 v[160:163], v215
	v_mfma_f32_16x16x32_bf16 v[96:99], v[176:179], v[204:207], v[96:99]
	v_mfma_f32_16x16x32_bf16 v[100:103], v[176:179], v[222:225], v[100:103]
	v_dot2c_f32_bf16_e32 v198, v176, v176
	v_dot2c_f32_bf16_e32 v198, v177, v177
	v_mfma_f32_16x16x32_bf16 v[104:107], v[176:179], v[226:229], v[104:107]
	v_mfma_f32_16x16x32_bf16 v[108:111], v[176:179], v[230:233], v[108:111]
	v_dot2c_f32_bf16_e32 v198, v178, v178
	v_dot2c_f32_bf16_e32 v198, v179, v179
	v_mfma_f32_16x16x32_bf16 v[112:115], v[176:179], v[234:237], v[112:115]
	v_mfma_f32_16x16x32_bf16 v[116:119], v[176:179], v[238:241], v[116:119]
	v_mfma_f32_16x16x32_bf16 v[120:123], v[176:179], v[242:245], v[120:123]
	v_mfma_f32_16x16x32_bf16 v[124:127], v[176:179], v[246:249], v[124:127]
	ds_read_b128 v[176:179], v215 offset:2048
	v_mfma_f32_16x16x32_bf16 v[0:3], v[180:183], v[204:207], v[0:3]
	v_mfma_f32_16x16x32_bf16 v[4:7], v[180:183], v[222:225], v[4:7]
	v_dot2c_f32_bf16_e32 v171, v180, v180
	v_dot2c_f32_bf16_e32 v171, v181, v181
	v_mfma_f32_16x16x32_bf16 v[8:11], v[180:183], v[226:229], v[8:11]
	v_mfma_f32_16x16x32_bf16 v[12:15], v[180:183], v[230:233], v[12:15]
	v_dot2c_f32_bf16_e32 v171, v182, v182
	v_dot2c_f32_bf16_e32 v171, v183, v183
	v_mfma_f32_16x16x32_bf16 v[16:19], v[180:183], v[234:237], v[16:19]
	v_mfma_f32_16x16x32_bf16 v[20:23], v[180:183], v[238:241], v[20:23]
	v_mfma_f32_16x16x32_bf16 v[24:27], v[180:183], v[242:245], v[24:27]
	v_mfma_f32_16x16x32_bf16 v[28:31], v[180:183], v[246:249], v[28:31]
	ds_read_b128 v[180:183], v215 offset:4096
	s_waitcnt lgkmcnt(3)
	v_mfma_f32_16x16x32_bf16 v[32:35], v[200:203], v[204:207], v[32:35]
	ds_read_b128 v[204:207], v197
	v_mfma_f32_16x16x32_bf16 v[36:39], v[200:203], v[222:225], v[36:39]
	v_dot2c_f32_bf16_e32 v164, v200, v200
	v_dot2c_f32_bf16_e32 v164, v201, v201
	ds_read_b128 v[222:225], v197 offset:2048
	v_mfma_f32_16x16x32_bf16 v[40:43], v[200:203], v[226:229], v[40:43]
	ds_read_b128 v[226:229], v197 offset:4096
	v_mfma_f32_16x16x32_bf16 v[44:47], v[200:203], v[230:233], v[44:47]
	v_dot2c_f32_bf16_e32 v164, v202, v202
	v_dot2c_f32_bf16_e32 v164, v203, v203
	ds_read_b128 v[230:233], v197 offset:6144
	v_mfma_f32_16x16x32_bf16 v[48:51], v[200:203], v[234:237], v[48:51]
	ds_read_b128 v[234:237], v197 offset:8192
	v_mfma_f32_16x16x32_bf16 v[52:55], v[200:203], v[238:241], v[52:55]
	ds_read_b128 v[238:241], v197 offset:10240
	v_mfma_f32_16x16x32_bf16 v[56:59], v[200:203], v[242:245], v[56:59]
	ds_read_b128 v[242:245], v197 offset:12288
	v_mfma_f32_16x16x32_bf16 v[60:63], v[200:203], v[246:249], v[60:63]
	ds_read_b128 v[246:249], v197 offset:14336
	ds_read_b128 v[200:203], v215 offset:6144
	s_waitcnt lgkmcnt(8)
	v_mfma_f32_16x16x32_bf16 v[64:67], v[160:163], v[204:207], v[64:67]
	s_waitcnt lgkmcnt(7)
	v_mfma_f32_16x16x32_bf16 v[68:71], v[160:163], v[222:225], v[68:71]
	v_dot2c_f32_bf16_e32 v199, v160, v160
	v_dot2c_f32_bf16_e32 v199, v161, v161
	s_waitcnt lgkmcnt(6)
	v_mfma_f32_16x16x32_bf16 v[72:75], v[160:163], v[226:229], v[72:75]
	s_waitcnt lgkmcnt(5)
	v_mfma_f32_16x16x32_bf16 v[76:79], v[160:163], v[230:233], v[76:79]
	v_dot2c_f32_bf16_e32 v199, v162, v162
	v_dot2c_f32_bf16_e32 v199, v163, v163
	s_waitcnt lgkmcnt(4)
	v_mfma_f32_16x16x32_bf16 v[80:83], v[160:163], v[234:237], v[80:83]
	s_waitcnt lgkmcnt(3)
	v_mfma_f32_16x16x32_bf16 v[84:87], v[160:163], v[238:241], v[84:87]
	s_waitcnt lgkmcnt(2)
	v_mfma_f32_16x16x32_bf16 v[88:91], v[160:163], v[242:245], v[88:91]
	s_waitcnt lgkmcnt(1)
	v_mfma_f32_16x16x32_bf16 v[92:95], v[160:163], v[246:249], v[92:95]
	s_waitcnt vmcnt(0) lgkmcnt(0)
	s_barrier
; DI void lds_barrier() { asm volatile("s_waitcnt lgkmcnt(0)\n\ts_barrier" ::: "memory"); }
; #define G_LOAD(RA, RB, KT) { size_t as_ = astep, bs_ = bstep; asm volatile("" : "+s"(as_), "+s"(bs_)); \
;       _Pragma("unroll") for (int i = 0; i < 4; ++i) { RA[i] = *(const u32x4*)(Ag + i * as_ + (KT) * 64); RB[i] = *(const u32x4*)(Bg + i * bs_ + (KT) * 64); } }
; DI void gemm_run(const GemmCfg c, char* smem, float* const g_h, u16* const g_hb, float* const g_out, const int final_out) {
;     ...
;     G_LOAD(ra0, rb0, 0);
;     __syncthreads();
;     G_STORE(ra0, rb0, 0);
;     G_LOAD(ra0, rb0, 1);
;     lds_barrier();
;     int kt = 0;
;     for (; kt + 3 < nk; kt += 2) {
;       K_STEP(0, 1, kt + 2, true, true);
;       lds_barrier();
;       K_STEP(1, 0, kt + 3, true, true);
;       lds_barrier();
	s_add_u32 m0, s8, 0x0
	ds_read_b128 v[160:163], v194 offset:36864
	v_mfma_f32_16x16x32_bf16 v[96:99], v[176:179], v[204:207], v[96:99]
	global_load_lds_dwordx4 v130, s[4:5]
	v_mfma_f32_16x16x32_bf16 v[100:103], v[176:179], v[222:225], v[100:103]
	v_dot2c_f32_bf16_e32 v198, v176, v176
	v_dot2c_f32_bf16_e32 v198, v177, v177
	s_add_u32 m0, s8, 0x12000
	v_mfma_f32_16x16x32_bf16 v[104:107], v[176:179], v[226:229], v[104:107]
	global_load_lds_dwordx4 v134, s[6:7]
	v_mfma_f32_16x16x32_bf16 v[108:111], v[176:179], v[230:233], v[108:111]
	v_dot2c_f32_bf16_e32 v198, v178, v178
	v_dot2c_f32_bf16_e32 v198, v179, v179
	s_add_u32 m0, s8, 0x400
	v_mfma_f32_16x16x32_bf16 v[112:115], v[176:179], v[234:237], v[112:115]
	global_load_lds_dwordx4 v131, s[4:5]
	v_mfma_f32_16x16x32_bf16 v[116:119], v[176:179], v[238:241], v[116:119]
	s_add_u32 m0, s8, 0x12400
	v_mfma_f32_16x16x32_bf16 v[120:123], v[176:179], v[242:245], v[120:123]
	global_load_lds_dwordx4 v135, s[6:7]
	v_mfma_f32_16x16x32_bf16 v[124:127], v[176:179], v[246:249], v[124:127]
	s_add_u32 m0, s8, 0x800
	ds_read_b128 v[176:179], v194 offset:38912
	v_mfma_f32_16x16x32_bf16 v[0:3], v[180:183], v[204:207], v[0:3]
	global_load_lds_dwordx4 v132, s[4:5]
	v_mfma_f32_16x16x32_bf16 v[4:7], v[180:183], v[222:225], v[4:7]
	v_dot2c_f32_bf16_e32 v171, v180, v180
	v_dot2c_f32_bf16_e32 v171, v181, v181
	s_add_u32 m0, s8, 0x12800
	v_mfma_f32_16x16x32_bf16 v[8:11], v[180:183], v[226:229], v[8:11]
	global_load_lds_dwordx4 v136, s[6:7]
	v_mfma_f32_16x16x32_bf16 v[12:15], v[180:183], v[230:233], v[12:15]
	v_dot2c_f32_bf16_e32 v171, v182, v182
	v_dot2c_f32_bf16_e32 v171, v183, v183
	s_add_u32 m0, s8, 0xc00
	v_mfma_f32_16x16x32_bf16 v[16:19], v[180:183], v[234:237], v[16:19]
	global_load_lds_dwordx4 v133, s[4:5]
	v_mfma_f32_16x16x32_bf16 v[20:23], v[180:183], v[238:241], v[20:23]
	s_add_u32 m0, s8, 0x12c00
	v_mfma_f32_16x16x32_bf16 v[24:27], v[180:183], v[242:245], v[24:27]
	global_load_lds_dwordx4 v137, s[6:7]
	v_mfma_f32_16x16x32_bf16 v[28:31], v[180:183], v[246:249], v[28:31]
	s_add_u32 s4, s4, 0x80
	s_addc_u32 s5, s5, 0
	s_add_u32 s6, s6, 0x80
	s_addc_u32 s7, s7, 0
	ds_read_b128 v[180:183], v194 offset:40960
	v_mfma_f32_16x16x32_bf16 v[32:35], v[200:203], v[204:207], v[32:35]
	ds_read_b128 v[204:207], v195 offset:36864
	v_mfma_f32_16x16x32_bf16 v[36:39], v[200:203], v[222:225], v[36:39]
	v_dot2c_f32_bf16_e32 v164, v200, v200
	v_dot2c_f32_bf16_e32 v164, v201, v201
	ds_read_b128 v[222:225], v195 offset:38912
	v_mfma_f32_16x16x32_bf16 v[40:43], v[200:203], v[226:229], v[40:43]
	ds_read_b128 v[226:229], v195 offset:40960
	v_mfma_f32_16x16x32_bf16 v[44:47], v[200:203], v[230:233], v[44:47]
	v_dot2c_f32_bf16_e32 v164, v202, v202
	v_dot2c_f32_bf16_e32 v164, v203, v203
	ds_read_b128 v[230:233], v195 offset:43008
	v_mfma_f32_16x16x32_bf16 v[48:51], v[200:203], v[234:237], v[48:51]
	ds_read_b128 v[234:237], v195 offset:45056
	v_mfma_f32_16x16x32_bf16 v[52:55], v[200:203], v[238:241], v[52:55]
	ds_read_b128 v[238:241], v195 offset:47104
	v_mfma_f32_16x16x32_bf16 v[56:59], v[200:203], v[242:245], v[56:59]
	ds_read_b128 v[242:245], v195 offset:49152
	v_mfma_f32_16x16x32_bf16 v[60:63], v[200:203], v[246:249], v[60:63]
	ds_read_b128 v[246:249], v195 offset:51200
	ds_read_b128 v[200:203], v194 offset:43008
	s_waitcnt lgkmcnt(8)
	v_mfma_f32_16x16x32_bf16 v[64:67], v[160:163], v[204:207], v[64:67]
	s_waitcnt lgkmcnt(7)
	v_mfma_f32_16x16x32_bf16 v[68:71], v[160:163], v[222:225], v[68:71]
	v_dot2c_f32_bf16_e32 v199, v160, v160
	v_dot2c_f32_bf16_e32 v199, v161, v161
	s_waitcnt lgkmcnt(6)
	v_mfma_f32_16x16x32_bf16 v[72:75], v[160:163], v[226:229], v[72:75]
	s_waitcnt lgkmcnt(5)
	v_mfma_f32_16x16x32_bf16 v[76:79], v[160:163], v[230:233], v[76:79]
	v_dot2c_f32_bf16_e32 v199, v162, v162
	v_dot2c_f32_bf16_e32 v199, v163, v163
	s_waitcnt lgkmcnt(4)
	v_mfma_f32_16x16x32_bf16 v[80:83], v[160:163], v[234:237], v[80:83]
	s_waitcnt lgkmcnt(3)
	v_mfma_f32_16x16x32_bf16 v[84:87], v[160:163], v[238:241], v[84:87]
	s_waitcnt lgkmcnt(2)
	v_mfma_f32_16x16x32_bf16 v[88:91], v[160:163], v[242:245], v[88:91]
	s_waitcnt lgkmcnt(1)
	v_mfma_f32_16x16x32_bf16 v[92:95], v[160:163], v[246:249], v[92:95]
	ds_read_b128 v[160:163], v215 offset:36864
	v_mfma_f32_16x16x32_bf16 v[96:99], v[176:179], v[204:207], v[96:99]
	v_mfma_f32_16x16x32_bf16 v[100:103], v[176:179], v[222:225], v[100:103]
	v_dot2c_f32_bf16_e32 v198, v176, v176
	v_dot2c_f32_bf16_e32 v198, v177, v177
	v_mfma_f32_16x16x32_bf16 v[104:107], v[176:179], v[226:229], v[104:107]
	v_mfma_f32_16x16x32_bf16 v[108:111], v[176:179], v[230:233], v[108:111]
	v_dot2c_f32_bf16_e32 v198, v178, v178
	v_dot2c_f32_bf16_e32 v198, v179, v179
	v_mfma_f32_16x16x32_bf16 v[112:115], v[176:179], v[234:237], v[112:115]
	v_mfma_f32_16x16x32_bf16 v[116:119], v[176:179], v[238:241], v[116:119]
	v_mfma_f32_16x16x32_bf16 v[120:123], v[176:179], v[242:245], v[120:123]
	v_mfma_f32_16x16x32_bf16 v[124:127], v[176:179], v[246:249], v[124:127]
	ds_read_b128 v[176:179], v215 offset:38912
	v_mfma_f32_16x16x32_bf16 v[0:3], v[180:183], v[204:207], v[0:3]
	v_mfma_f32_16x16x32_bf16 v[4:7], v[180:183], v[222:225], v[4:7]
	v_dot2c_f32_bf16_e32 v171, v180, v180
	v_dot2c_f32_bf16_e32 v171, v181, v181
	v_mfma_f32_16x16x32_bf16 v[8:11], v[180:183], v[226:229], v[8:11]
	v_mfma_f32_16x16x32_bf16 v[12:15], v[180:183], v[230:233], v[12:15]
	v_dot2c_f32_bf16_e32 v171, v182, v182
	v_dot2c_f32_bf16_e32 v171, v183, v183
	v_mfma_f32_16x16x32_bf16 v[16:19], v[180:183], v[234:237], v[16:19]
	v_mfma_f32_16x16x32_bf16 v[20:23], v[180:183], v[238:241], v[20:23]
	v_mfma_f32_16x16x32_bf16 v[24:27], v[180:183], v[242:245], v[24:27]
	v_mfma_f32_16x16x32_bf16 v[28:31], v[180:183], v[246:249], v[28:31]
	ds_read_b128 v[180:183], v215 offset:40960
	s_waitcnt lgkmcnt(3)
; DI void lds_barrier() { asm volatile("s_waitcnt lgkmcnt(0)\n\ts_barrier" ::: "memory"); }
; #define G_LOAD(RA, RB, KT) { size_t as_ = astep, bs_ = bstep; asm volatile("" : "+s"(as_), "+s"(bs_)); \
;       _Pragma("unroll") for (int i = 0; i < 4; ++i) { RA[i] = *(const u32x4*)(Ag + i * as_ + (KT) * 64); RB[i] = *(const u32x4*)(Bg + i * bs_ + (KT) * 64); } }
; DI void gemm_run(const GemmCfg c, char* smem, float* const g_h, u16* const g_hb, float* const g_out, const int final_out) {
;     ...
;     G_LOAD(ra0, rb0, 0);
;     __syncthreads();
;     G_STORE(ra0, rb0, 0);
;     G_LOAD(ra0, rb0, 1);
;     lds_barrier();
;     int kt = 0;
;     for (; kt + 3 < nk; kt += 2) {
;       K_STEP(0, 1, kt + 2, true, true);
;       lds_barrier();
;       K_STEP(1, 0, kt + 3, true, true);
;       lds_barrier();
	v_mfma_f32_16x16x32_bf16 v[32:35], v[200:203], v[204:207], v[32:35]
	ds_read_b128 v[204:207], v197 offset:36864
	v_mfma_f32_16x16x32_bf16 v[36:39], v[200:203], v[222:225], v[36:39]
	v_dot2c_f32_bf16_e32 v164, v200, v200
	v_dot2c_f32_bf16_e32 v164, v201, v201
	ds_read_b128 v[222:225], v197 offset:38912
	v_mfma_f32_16x16x32_bf16 v[40:43], v[200:203], v[226:229], v[40:43]
	ds_read_b128 v[226:229], v197 offset:40960
	v_mfma_f32_16x16x32_bf16 v[44:47], v[200:203], v[230:233], v[44:47]
	v_dot2c_f32_bf16_e32 v164, v202, v202
	v_dot2c_f32_bf16_e32 v164, v203, v203
	ds_read_b128 v[230:233], v197 offset:43008
	v_mfma_f32_16x16x32_bf16 v[48:51], v[200:203], v[234:237], v[48:51]
	ds_read_b128 v[234:237], v197 offset:45056
	v_mfma_f32_16x16x32_bf16 v[52:55], v[200:203], v[238:241], v[52:55]
	ds_read_b128 v[238:241], v197 offset:47104
	v_mfma_f32_16x16x32_bf16 v[56:59], v[200:203], v[242:245], v[56:59]
	ds_read_b128 v[242:245], v197 offset:49152
	v_mfma_f32_16x16x32_bf16 v[60:63], v[200:203], v[246:249], v[60:63]
	ds_read_b128 v[246:249], v197 offset:51200
	ds_read_b128 v[200:203], v215 offset:43008
	s_waitcnt lgkmcnt(8)
	v_mfma_f32_16x16x32_bf16 v[64:67], v[160:163], v[204:207], v[64:67]
	s_waitcnt lgkmcnt(7)
	v_mfma_f32_16x16x32_bf16 v[68:71], v[160:163], v[222:225], v[68:71]
	v_dot2c_f32_bf16_e32 v199, v160, v160
	v_dot2c_f32_bf16_e32 v199, v161, v161
	s_waitcnt lgkmcnt(6)
	v_mfma_f32_16x16x32_bf16 v[72:75], v[160:163], v[226:229], v[72:75]
	s_waitcnt lgkmcnt(5)
	v_mfma_f32_16x16x32_bf16 v[76:79], v[160:163], v[230:233], v[76:79]
	v_dot2c_f32_bf16_e32 v199, v162, v162
	v_dot2c_f32_bf16_e32 v199, v163, v163
	s_waitcnt lgkmcnt(4)
	v_mfma_f32_16x16x32_bf16 v[80:83], v[160:163], v[234:237], v[80:83]
	s_waitcnt lgkmcnt(3)
	v_mfma_f32_16x16x32_bf16 v[84:87], v[160:163], v[238:241], v[84:87]
	s_waitcnt lgkmcnt(2)
	v_mfma_f32_16x16x32_bf16 v[88:91], v[160:163], v[242:245], v[88:91]
	s_waitcnt lgkmcnt(1)
	v_mfma_f32_16x16x32_bf16 v[92:95], v[160:163], v[246:249], v[92:95]
	s_waitcnt vmcnt(0) lgkmcnt(0)
	s_barrier
	s_add_u32 m0, s8, 0x9000
	ds_read_b128 v[160:163], v194
	v_mfma_f32_16x16x32_bf16 v[96:99], v[176:179], v[204:207], v[96:99]
	global_load_lds_dwordx4 v130, s[4:5]
	v_mfma_f32_16x16x32_bf16 v[100:103], v[176:179], v[222:225], v[100:103]
	v_dot2c_f32_bf16_e32 v198, v176, v176
	v_dot2c_f32_bf16_e32 v198, v177, v177
	s_add_u32 m0, s8, 0x1b000
	v_mfma_f32_16x16x32_bf16 v[104:107], v[176:179], v[226:229], v[104:107]
	global_load_lds_dwordx4 v134, s[6:7]
	v_mfma_f32_16x16x32_bf16 v[108:111], v[176:179], v[230:233], v[108:111]
	v_dot2c_f32_bf16_e32 v198, v178, v178
	v_dot2c_f32_bf16_e32 v198, v179, v179
	s_add_u32 m0, s8, 0x9400
	v_mfma_f32_16x16x32_bf16 v[112:115], v[176:179], v[234:237], v[112:115]
	global_load_lds_dwordx4 v131, s[4:5]
	v_mfma_f32_16x16x32_bf16 v[116:119], v[176:179], v[238:241], v[116:119]
	s_add_u32 m0, s8, 0x1b400
	v_mfma_f32_16x16x32_bf16 v[120:123], v[176:179], v[242:245], v[120:123]
	global_load_lds_dwordx4 v135, s[6:7]
	v_mfma_f32_16x16x32_bf16 v[124:127], v[176:179], v[246:249], v[124:127]
	s_add_u32 m0, s8, 0x9800
	ds_read_b128 v[176:179], v194 offset:2048
	v_mfma_f32_16x16x32_bf16 v[0:3], v[180:183], v[204:207], v[0:3]
	global_load_lds_dwordx4 v132, s[4:5]
	v_mfma_f32_16x16x32_bf16 v[4:7], v[180:183], v[222:225], v[4:7]
	v_dot2c_f32_bf16_e32 v171, v180, v180
	v_dot2c_f32_bf16_e32 v171, v181, v181
	s_add_u32 m0, s8, 0x1b800
	v_mfma_f32_16x16x32_bf16 v[8:11], v[180:183], v[226:229], v[8:11]
	global_load_lds_dwordx4 v136, s[6:7]
	v_mfma_f32_16x16x32_bf16 v[12:15], v[180:183], v[230:233], v[12:15]
	v_dot2c_f32_bf16_e32 v171, v182, v182
	v_dot2c_f32_bf16_e32 v171, v183, v183
	s_add_u32 m0, s8, 0x9c00
	v_mfma_f32_16x16x32_bf16 v[16:19], v[180:183], v[234:237], v[16:19]
	global_load_lds_dwordx4 v133, s[4:5]
	v_mfma_f32_16x16x32_bf16 v[20:23], v[180:183], v[238:241], v[20:23]
	s_add_u32 m0, s8, 0x1bc00
	v_mfma_f32_16x16x32_bf16 v[24:27], v[180:183], v[242:245], v[24:27]
	global_load_lds_dwordx4 v137, s[6:7]
	v_mfma_f32_16x16x32_bf16 v[28:31], v[180:183], v[246:249], v[28:31]
	s_add_u32 s4, s4, 0x80
	s_addc_u32 s5, s5, 0
	s_add_u32 s6, s6, 0x80
	s_addc_u32 s7, s7, 0
	ds_read_b128 v[180:183], v194 offset:4096
	v_mfma_f32_16x16x32_bf16 v[32:35], v[200:203], v[204:207], v[32:35]
	ds_read_b128 v[204:207], v195
	v_mfma_f32_16x16x32_bf16 v[36:39], v[200:203], v[222:225], v[36:39]
	v_dot2c_f32_bf16_e32 v164, v200, v200
	v_dot2c_f32_bf16_e32 v164, v201, v201
	ds_read_b128 v[222:225], v195 offset:2048
	v_mfma_f32_16x16x32_bf16 v[40:43], v[200:203], v[226:229], v[40:43]
	ds_read_b128 v[226:229], v195 offset:4096
	v_mfma_f32_16x16x32_bf16 v[44:47], v[200:203], v[230:233], v[44:47]
	v_dot2c_f32_bf16_e32 v164, v202, v202
	v_dot2c_f32_bf16_e32 v164, v203, v203
	ds_read_b128 v[230:233], v195 offset:6144
	v_mfma_f32_16x16x32_bf16 v[48:51], v[200:203], v[234:237], v[48:51]
	ds_read_b128 v[234:237], v195 offset:8192
	v_mfma_f32_16x16x32_bf16 v[52:55], v[200:203], v[238:241], v[52:55]
	ds_read_b128 v[238:241], v195 offset:10240
	v_mfma_f32_16x16x32_bf16 v[56:59], v[200:203], v[242:245], v[56:59]
	ds_read_b128 v[242:245], v195 offset:12288
	v_mfma_f32_16x16x32_bf16 v[60:63], v[200:203], v[246:249], v[60:63]
	ds_read_b128 v[246:249], v195 offset:14336
	ds_read_b128 v[200:203], v194 offset:6144
	s_add_i32 s1, s1, 2
	s_cmp_lt_i32 s1, s0
	s_cbranch_scc1 .LBB0_112
; DI void lds_barrier() { asm volatile("s_waitcnt lgkmcnt(0)\n\ts_barrier" ::: "memory"); }
; DI void gemm_run(const GemmCfg c, char* smem, float* const g_h, u16* const g_hb, float* const g_out, const int final_out) {
;     ...
;     K_STEP(0, 1, 0, true, false);
;     lds_barrier();
;     K_STEP(1, 0, 0, false, false);
;     lds_barrier();
	s_waitcnt lgkmcnt(8)
	v_mfma_f32_16x16x32_bf16 v[64:67], v[160:163], v[204:207], v[64:67]
	s_waitcnt lgkmcnt(7)
	v_mfma_f32_16x16x32_bf16 v[68:71], v[160:163], v[222:225], v[68:71]
	v_dot2c_f32_bf16_e32 v199, v160, v160
	v_dot2c_f32_bf16_e32 v199, v161, v161
	s_waitcnt lgkmcnt(6)
	v_mfma_f32_16x16x32_bf16 v[72:75], v[160:163], v[226:229], v[72:75]
	s_waitcnt lgkmcnt(5)
	v_mfma_f32_16x16x32_bf16 v[76:79], v[160:163], v[230:233], v[76:79]
	v_dot2c_f32_bf16_e32 v199, v162, v162
	v_dot2c_f32_bf16_e32 v199, v163, v163
	s_waitcnt lgkmcnt(4)
	v_mfma_f32_16x16x32_bf16 v[80:83], v[160:163], v[234:237], v[80:83]
	s_waitcnt lgkmcnt(3)
	v_mfma_f32_16x16x32_bf16 v[84:87], v[160:163], v[238:241], v[84:87]
	s_waitcnt lgkmcnt(2)
	v_mfma_f32_16x16x32_bf16 v[88:91], v[160:163], v[242:245], v[88:91]
	s_waitcnt lgkmcnt(1)
	v_mfma_f32_16x16x32_bf16 v[92:95], v[160:163], v[246:249], v[92:95]
	ds_read_b128 v[160:163], v215
	v_mfma_f32_16x16x32_bf16 v[96:99], v[176:179], v[204:207], v[96:99]
	v_mfma_f32_16x16x32_bf16 v[100:103], v[176:179], v[222:225], v[100:103]
	v_dot2c_f32_bf16_e32 v198, v176, v176
	v_dot2c_f32_bf16_e32 v198, v177, v177
	v_mfma_f32_16x16x32_bf16 v[104:107], v[176:179], v[226:229], v[104:107]
	v_mfma_f32_16x16x32_bf16 v[108:111], v[176:179], v[230:233], v[108:111]
	v_dot2c_f32_bf16_e32 v198, v178, v178
	v_dot2c_f32_bf16_e32 v198, v179, v179
	v_mfma_f32_16x16x32_bf16 v[112:115], v[176:179], v[234:237], v[112:115]
	v_mfma_f32_16x16x32_bf16 v[116:119], v[176:179], v[238:241], v[116:119]
	v_mfma_f32_16x16x32_bf16 v[120:123], v[176:179], v[242:245], v[120:123]
	v_mfma_f32_16x16x32_bf16 v[124:127], v[176:179], v[246:249], v[124:127]
	ds_read_b128 v[176:179], v215 offset:2048
	v_mfma_f32_16x16x32_bf16 v[0:3], v[180:183], v[204:207], v[0:3]
	v_mfma_f32_16x16x32_bf16 v[4:7], v[180:183], v[222:225], v[4:7]
	v_dot2c_f32_bf16_e32 v171, v180, v180
	v_dot2c_f32_bf16_e32 v171, v181, v181
	v_mfma_f32_16x16x32_bf16 v[8:11], v[180:183], v[226:229], v[8:11]
	v_mfma_f32_16x16x32_bf16 v[12:15], v[180:183], v[230:233], v[12:15]
	v_dot2c_f32_bf16_e32 v171, v182, v182
	v_dot2c_f32_bf16_e32 v171, v183, v183
	v_mfma_f32_16x16x32_bf16 v[16:19], v[180:183], v[234:237], v[16:19]
	v_mfma_f32_16x16x32_bf16 v[20:23], v[180:183], v[238:241], v[20:23]
	v_mfma_f32_16x16x32_bf16 v[24:27], v[180:183], v[242:245], v[24:27]
	v_mfma_f32_16x16x32_bf16 v[28:31], v[180:183], v[246:249], v[28:31]
	ds_read_b128 v[180:183], v215 offset:4096
	s_waitcnt lgkmcnt(3)
	v_mfma_f32_16x16x32_bf16 v[32:35], v[200:203], v[204:207], v[32:35]
	ds_read_b128 v[204:207], v197
	v_mfma_f32_16x16x32_bf16 v[36:39], v[200:203], v[222:225], v[36:39]
	v_dot2c_f32_bf16_e32 v164, v200, v200
	v_dot2c_f32_bf16_e32 v164, v201, v201
	ds_read_b128 v[222:225], v197 offset:2048
	v_mfma_f32_16x16x32_bf16 v[40:43], v[200:203], v[226:229], v[40:43]
	ds_read_b128 v[226:229], v197 offset:4096
	v_mfma_f32_16x16x32_bf16 v[44:47], v[200:203], v[230:233], v[44:47]
	v_dot2c_f32_bf16_e32 v164, v202, v202
	v_dot2c_f32_bf16_e32 v164, v203, v203
	ds_read_b128 v[230:233], v197 offset:6144
	v_mfma_f32_16x16x32_bf16 v[48:51], v[200:203], v[234:237], v[48:51]
	ds_read_b128 v[234:237], v197 offset:8192
	v_mfma_f32_16x16x32_bf16 v[52:55], v[200:203], v[238:241], v[52:55]
	ds_read_b128 v[238:241], v197 offset:10240
	v_mfma_f32_16x16x32_bf16 v[56:59], v[200:203], v[242:245], v[56:59]
	ds_read_b128 v[242:245], v197 offset:12288
	v_mfma_f32_16x16x32_bf16 v[60:63], v[200:203], v[246:249], v[60:63]
	ds_read_b128 v[246:249], v197 offset:14336
	ds_read_b128 v[200:203], v215 offset:6144
	s_waitcnt lgkmcnt(8)
	v_mfma_f32_16x16x32_bf16 v[64:67], v[160:163], v[204:207], v[64:67]
	s_waitcnt lgkmcnt(7)
	v_mfma_f32_16x16x32_bf16 v[68:71], v[160:163], v[222:225], v[68:71]
	v_dot2c_f32_bf16_e32 v199, v160, v160
	v_dot2c_f32_bf16_e32 v199, v161, v161
	s_waitcnt lgkmcnt(6)
	v_mfma_f32_16x16x32_bf16 v[72:75], v[160:163], v[226:229], v[72:75]
	s_waitcnt lgkmcnt(5)
	v_mfma_f32_16x16x32_bf16 v[76:79], v[160:163], v[230:233], v[76:79]
	v_dot2c_f32_bf16_e32 v199, v162, v162
	v_dot2c_f32_bf16_e32 v199, v163, v163
	s_waitcnt lgkmcnt(4)
	v_mfma_f32_16x16x32_bf16 v[80:83], v[160:163], v[234:237], v[80:83]
	s_waitcnt lgkmcnt(3)
	v_mfma_f32_16x16x32_bf16 v[84:87], v[160:163], v[238:241], v[84:87]
	s_waitcnt lgkmcnt(2)
	v_mfma_f32_16x16x32_bf16 v[88:91], v[160:163], v[242:245], v[88:91]
	s_waitcnt lgkmcnt(1)
	v_mfma_f32_16x16x32_bf16 v[92:95], v[160:163], v[246:249], v[92:95]
	s_waitcnt vmcnt(0) lgkmcnt(0)
	s_barrier
; DI void lds_barrier() { asm volatile("s_waitcnt lgkmcnt(0)\n\ts_barrier" ::: "memory"); }
; DI void gemm_run(const GemmCfg c, char* smem, float* const g_h, u16* const g_hb, float* const g_out, const int final_out) {
;     ...
;     K_STEP(0, 1, 0, true, false);
;     lds_barrier();
;     K_STEP(1, 0, 0, false, false);
;     lds_barrier();
	ds_read_b128 v[160:163], v194 offset:36864
	v_mfma_f32_16x16x32_bf16 v[96:99], v[176:179], v[204:207], v[96:99]
	v_mfma_f32_16x16x32_bf16 v[100:103], v[176:179], v[222:225], v[100:103]
	v_dot2c_f32_bf16_e32 v198, v176, v176
	v_dot2c_f32_bf16_e32 v198, v177, v177
	v_mfma_f32_16x16x32_bf16 v[104:107], v[176:179], v[226:229], v[104:107]
	v_mfma_f32_16x16x32_bf16 v[108:111], v[176:179], v[230:233], v[108:111]
	v_dot2c_f32_bf16_e32 v198, v178, v178
	v_dot2c_f32_bf16_e32 v198, v179, v179
	v_mfma_f32_16x16x32_bf16 v[112:115], v[176:179], v[234:237], v[112:115]
	v_mfma_f32_16x16x32_bf16 v[116:119], v[176:179], v[238:241], v[116:119]
	v_mfma_f32_16x16x32_bf16 v[120:123], v[176:179], v[242:245], v[120:123]
	v_mfma_f32_16x16x32_bf16 v[124:127], v[176:179], v[246:249], v[124:127]
	ds_read_b128 v[176:179], v194 offset:38912
	v_mfma_f32_16x16x32_bf16 v[0:3], v[180:183], v[204:207], v[0:3]
	v_mfma_f32_16x16x32_bf16 v[4:7], v[180:183], v[222:225], v[4:7]
	v_dot2c_f32_bf16_e32 v171, v180, v180
	v_dot2c_f32_bf16_e32 v171, v181, v181
	v_mfma_f32_16x16x32_bf16 v[8:11], v[180:183], v[226:229], v[8:11]
	v_mfma_f32_16x16x32_bf16 v[12:15], v[180:183], v[230:233], v[12:15]
	v_dot2c_f32_bf16_e32 v171, v182, v182
	v_dot2c_f32_bf16_e32 v171, v183, v183
	v_mfma_f32_16x16x32_bf16 v[16:19], v[180:183], v[234:237], v[16:19]
	v_mfma_f32_16x16x32_bf16 v[20:23], v[180:183], v[238:241], v[20:23]
	v_mfma_f32_16x16x32_bf16 v[24:27], v[180:183], v[242:245], v[24:27]
	v_mfma_f32_16x16x32_bf16 v[28:31], v[180:183], v[246:249], v[28:31]
	ds_read_b128 v[180:183], v194 offset:40960
	v_mfma_f32_16x16x32_bf16 v[32:35], v[200:203], v[204:207], v[32:35]
	ds_read_b128 v[204:207], v195 offset:36864
	v_mfma_f32_16x16x32_bf16 v[36:39], v[200:203], v[222:225], v[36:39]
	v_dot2c_f32_bf16_e32 v164, v200, v200
	v_dot2c_f32_bf16_e32 v164, v201, v201
	ds_read_b128 v[222:225], v195 offset:38912
	v_mfma_f32_16x16x32_bf16 v[40:43], v[200:203], v[226:229], v[40:43]
	ds_read_b128 v[226:229], v195 offset:40960
	v_mfma_f32_16x16x32_bf16 v[44:47], v[200:203], v[230:233], v[44:47]
	v_dot2c_f32_bf16_e32 v164, v202, v202
	v_dot2c_f32_bf16_e32 v164, v203, v203
	ds_read_b128 v[230:233], v195 offset:43008
	v_mfma_f32_16x16x32_bf16 v[48:51], v[200:203], v[234:237], v[48:51]
	ds_read_b128 v[234:237], v195 offset:45056
	v_mfma_f32_16x16x32_bf16 v[52:55], v[200:203], v[238:241], v[52:55]
	ds_read_b128 v[238:241], v195 offset:47104
	v_mfma_f32_16x16x32_bf16 v[56:59], v[200:203], v[242:245], v[56:59]
	ds_read_b128 v[242:245], v195 offset:49152
	v_mfma_f32_16x16x32_bf16 v[60:63], v[200:203], v[246:249], v[60:63]
	ds_read_b128 v[246:249], v195 offset:51200
	ds_read_b128 v[200:203], v194 offset:43008
	s_waitcnt lgkmcnt(8)
	v_mfma_f32_16x16x32_bf16 v[64:67], v[160:163], v[204:207], v[64:67]
	s_waitcnt lgkmcnt(7)
	v_mfma_f32_16x16x32_bf16 v[68:71], v[160:163], v[222:225], v[68:71]
	v_dot2c_f32_bf16_e32 v199, v160, v160
	v_dot2c_f32_bf16_e32 v199, v161, v161
	s_waitcnt lgkmcnt(6)
	v_mfma_f32_16x16x32_bf16 v[72:75], v[160:163], v[226:229], v[72:75]
	s_waitcnt lgkmcnt(5)
	v_mfma_f32_16x16x32_bf16 v[76:79], v[160:163], v[230:233], v[76:79]
	v_dot2c_f32_bf16_e32 v199, v162, v162
	v_dot2c_f32_bf16_e32 v199, v163, v163
	s_waitcnt lgkmcnt(4)
	v_mfma_f32_16x16x32_bf16 v[80:83], v[160:163], v[234:237], v[80:83]
	s_waitcnt lgkmcnt(3)
	v_mfma_f32_16x16x32_bf16 v[84:87], v[160:163], v[238:241], v[84:87]
	s_waitcnt lgkmcnt(2)
	v_mfma_f32_16x16x32_bf16 v[88:91], v[160:163], v[242:245], v[88:91]
	s_waitcnt lgkmcnt(1)
	v_mfma_f32_16x16x32_bf16 v[92:95], v[160:163], v[246:249], v[92:95]
	ds_read_b128 v[160:163], v215 offset:36864
	v_mfma_f32_16x16x32_bf16 v[96:99], v[176:179], v[204:207], v[96:99]
	v_mfma_f32_16x16x32_bf16 v[100:103], v[176:179], v[222:225], v[100:103]
	v_dot2c_f32_bf16_e32 v198, v176, v176
	v_dot2c_f32_bf16_e32 v198, v177, v177
	v_mfma_f32_16x16x32_bf16 v[104:107], v[176:179], v[226:229], v[104:107]
	v_mfma_f32_16x16x32_bf16 v[108:111], v[176:179], v[230:233], v[108:111]
	v_dot2c_f32_bf16_e32 v198, v178, v178
	v_dot2c_f32_bf16_e32 v198, v179, v179
	v_mfma_f32_16x16x32_bf16 v[112:115], v[176:179], v[234:237], v[112:115]
	v_mfma_f32_16x16x32_bf16 v[116:119], v[176:179], v[238:241], v[116:119]
	v_mfma_f32_16x16x32_bf16 v[120:123], v[176:179], v[242:245], v[120:123]
	v_mfma_f32_16x16x32_bf16 v[124:127], v[176:179], v[246:249], v[124:127]
	ds_read_b128 v[176:179], v215 offset:38912
	v_mfma_f32_16x16x32_bf16 v[0:3], v[180:183], v[204:207], v[0:3]
	v_mfma_f32_16x16x32_bf16 v[4:7], v[180:183], v[222:225], v[4:7]
	v_dot2c_f32_bf16_e32 v171, v180, v180
	v_dot2c_f32_bf16_e32 v171, v181, v181
	v_mfma_f32_16x16x32_bf16 v[8:11], v[180:183], v[226:229], v[8:11]
	v_mfma_f32_16x16x32_bf16 v[12:15], v[180:183], v[230:233], v[12:15]
	v_dot2c_f32_bf16_e32 v171, v182, v182
	v_dot2c_f32_bf16_e32 v171, v183, v183
	v_mfma_f32_16x16x32_bf16 v[16:19], v[180:183], v[234:237], v[16:19]
	v_mfma_f32_16x16x32_bf16 v[20:23], v[180:183], v[238:241], v[20:23]
	v_mfma_f32_16x16x32_bf16 v[24:27], v[180:183], v[242:245], v[24:27]
	v_mfma_f32_16x16x32_bf16 v[28:31], v[180:183], v[246:249], v[28:31]
	ds_read_b128 v[180:183], v215 offset:40960
	s_waitcnt lgkmcnt(3)
; DI void lds_barrier() { asm volatile("s_waitcnt lgkmcnt(0)\n\ts_barrier" ::: "memory"); }
; #define G_LOAD(RA, RB, KT) { size_t as_ = astep, bs_ = bstep; asm volatile("" : "+s"(as_), "+s"(bs_)); \
;       _Pragma("unroll") for (int i = 0; i < 4; ++i) { RA[i] = *(const u32x4*)(Ag + i * as_ + (KT) * 64); RB[i] = *(const u32x4*)(Bg + i * bs_ + (KT) * 64); } }
; DI void gemm_run(const GemmCfg c, char* smem, float* const g_h, u16* const g_hb, float* const g_out, const int final_out) {
;     ...
;     G_LOAD(ra0, rb0, 0);
;     __syncthreads();
;     G_STORE(ra0, rb0, 0);
;     G_LOAD(ra0, rb0, 1);
;     lds_barrier();
;     int kt = 0;
;     for (; kt + 3 < nk; kt += 2) {
;       K_STEP(0, 1, kt + 2, true, true);
;       lds_barrier();
;       K_STEP(1, 0, kt + 3, true, true);
;       lds_barrier();
;     }
;     K_STEP(0, 1, 0, true, false);
;     lds_barrier();
;     K_STEP(1, 0, 0, false, false);
;     lds_barrier();
	v_mfma_f32_16x16x32_bf16 v[32:35], v[200:203], v[204:207], v[32:35]
	ds_read_b128 v[204:207], v197 offset:36864
	v_mfma_f32_16x16x32_bf16 v[36:39], v[200:203], v[222:225], v[36:39]
	v_dot2c_f32_bf16_e32 v164, v200, v200
	v_dot2c_f32_bf16_e32 v164, v201, v201
	ds_read_b128 v[222:225], v197 offset:38912
	v_mfma_f32_16x16x32_bf16 v[40:43], v[200:203], v[226:229], v[40:43]
	ds_read_b128 v[226:229], v197 offset:40960
	v_mfma_f32_16x16x32_bf16 v[44:47], v[200:203], v[230:233], v[44:47]
	v_dot2c_f32_bf16_e32 v164, v202, v202
	v_dot2c_f32_bf16_e32 v164, v203, v203
	ds_read_b128 v[230:233], v197 offset:43008
	v_mfma_f32_16x16x32_bf16 v[48:51], v[200:203], v[234:237], v[48:51]
	ds_read_b128 v[234:237], v197 offset:45056
	v_mfma_f32_16x16x32_bf16 v[52:55], v[200:203], v[238:241], v[52:55]
	ds_read_b128 v[238:241], v197 offset:47104
	v_mfma_f32_16x16x32_bf16 v[56:59], v[200:203], v[242:245], v[56:59]
	ds_read_b128 v[242:245], v197 offset:49152
	v_mfma_f32_16x16x32_bf16 v[60:63], v[200:203], v[246:249], v[60:63]
	ds_read_b128 v[246:249], v197 offset:51200
	ds_read_b128 v[200:203], v215 offset:43008
	s_waitcnt lgkmcnt(8)
	v_mfma_f32_16x16x32_bf16 v[64:67], v[160:163], v[204:207], v[64:67]
	s_waitcnt lgkmcnt(7)
	v_mfma_f32_16x16x32_bf16 v[68:71], v[160:163], v[222:225], v[68:71]
	v_dot2c_f32_bf16_e32 v199, v160, v160
	v_dot2c_f32_bf16_e32 v199, v161, v161
	s_waitcnt lgkmcnt(6)
	v_mfma_f32_16x16x32_bf16 v[72:75], v[160:163], v[226:229], v[72:75]
	s_waitcnt lgkmcnt(5)
	v_mfma_f32_16x16x32_bf16 v[76:79], v[160:163], v[230:233], v[76:79]
	v_dot2c_f32_bf16_e32 v199, v162, v162
	v_dot2c_f32_bf16_e32 v199, v163, v163
	s_waitcnt lgkmcnt(4)
	v_mfma_f32_16x16x32_bf16 v[80:83], v[160:163], v[234:237], v[80:83]
	s_waitcnt lgkmcnt(3)
	v_mfma_f32_16x16x32_bf16 v[84:87], v[160:163], v[238:241], v[84:87]
	s_waitcnt lgkmcnt(2)
	v_mfma_f32_16x16x32_bf16 v[88:91], v[160:163], v[242:245], v[88:91]
	s_waitcnt lgkmcnt(1)
	v_mfma_f32_16x16x32_bf16 v[92:95], v[160:163], v[246:249], v[92:95]
	v_mfma_f32_16x16x32_bf16 v[96:99], v[176:179], v[204:207], v[96:99]
	v_mfma_f32_16x16x32_bf16 v[100:103], v[176:179], v[222:225], v[100:103]
	v_dot2c_f32_bf16_e32 v198, v176, v176
	v_dot2c_f32_bf16_e32 v198, v177, v177
	v_mfma_f32_16x16x32_bf16 v[104:107], v[176:179], v[226:229], v[104:107]
	v_mfma_f32_16x16x32_bf16 v[108:111], v[176:179], v[230:233], v[108:111]
	v_dot2c_f32_bf16_e32 v198, v178, v178
	v_dot2c_f32_bf16_e32 v198, v179, v179
	v_mfma_f32_16x16x32_bf16 v[112:115], v[176:179], v[234:237], v[112:115]
	v_mfma_f32_16x16x32_bf16 v[116:119], v[176:179], v[238:241], v[116:119]
	v_mfma_f32_16x16x32_bf16 v[120:123], v[176:179], v[242:245], v[120:123]
	v_mfma_f32_16x16x32_bf16 v[124:127], v[176:179], v[246:249], v[124:127]
	v_mfma_f32_16x16x32_bf16 v[0:3], v[180:183], v[204:207], v[0:3]
	v_mfma_f32_16x16x32_bf16 v[4:7], v[180:183], v[222:225], v[4:7]
	v_dot2c_f32_bf16_e32 v171, v180, v180
	v_dot2c_f32_bf16_e32 v171, v181, v181
	v_mfma_f32_16x16x32_bf16 v[8:11], v[180:183], v[226:229], v[8:11]
	v_mfma_f32_16x16x32_bf16 v[12:15], v[180:183], v[230:233], v[12:15]
	v_dot2c_f32_bf16_e32 v171, v182, v182
	v_dot2c_f32_bf16_e32 v171, v183, v183
	v_mfma_f32_16x16x32_bf16 v[16:19], v[180:183], v[234:237], v[16:19]
	v_mfma_f32_16x16x32_bf16 v[20:23], v[180:183], v[238:241], v[20:23]
	v_mfma_f32_16x16x32_bf16 v[24:27], v[180:183], v[242:245], v[24:27]
	v_mfma_f32_16x16x32_bf16 v[28:31], v[180:183], v[246:249], v[28:31]
	s_waitcnt lgkmcnt(0)
	v_mfma_f32_16x16x32_bf16 v[32:35], v[200:203], v[204:207], v[32:35]
	v_mfma_f32_16x16x32_bf16 v[36:39], v[200:203], v[222:225], v[36:39]
	v_dot2c_f32_bf16_e32 v164, v200, v200
	v_dot2c_f32_bf16_e32 v164, v201, v201
	v_mfma_f32_16x16x32_bf16 v[40:43], v[200:203], v[226:229], v[40:43]
	v_mfma_f32_16x16x32_bf16 v[44:47], v[200:203], v[230:233], v[44:47]
	v_dot2c_f32_bf16_e32 v164, v202, v202
	v_dot2c_f32_bf16_e32 v164, v203, v203
	v_mfma_f32_16x16x32_bf16 v[48:51], v[200:203], v[234:237], v[48:51]
	v_mfma_f32_16x16x32_bf16 v[52:55], v[200:203], v[238:241], v[52:55]
	v_mfma_f32_16x16x32_bf16 v[56:59], v[200:203], v[242:245], v[56:59]
	v_mfma_f32_16x16x32_bf16 v[60:63], v[200:203], v[246:249], v[60:63]
	s_branch .Lgemm_kdone
.Lgemm_kloop_n:
	s_waitcnt lgkmcnt(8)
	v_mfma_f32_16x16x32_bf16 v[64:67], v[160:163], v[204:207], v[64:67]
	s_waitcnt lgkmcnt(7)
	v_mfma_f32_16x16x32_bf16 v[68:71], v[160:163], v[222:225], v[68:71]
	s_waitcnt lgkmcnt(6)
	v_mfma_f32_16x16x32_bf16 v[72:75], v[160:163], v[226:229], v[72:75]
	s_waitcnt lgkmcnt(5)
	v_mfma_f32_16x16x32_bf16 v[76:79], v[160:163], v[230:233], v[76:79]
	s_waitcnt lgkmcnt(4)
	v_mfma_f32_16x16x32_bf16 v[80:83], v[160:163], v[234:237], v[80:83]
	s_waitcnt lgkmcnt(3)
	v_mfma_f32_16x16x32_bf16 v[84:87], v[160:163], v[238:241], v[84:87]
	s_waitcnt lgkmcnt(2)
	v_mfma_f32_16x16x32_bf16 v[88:91], v[160:163], v[242:245], v[88:91]
	s_waitcnt lgkmcnt(1)
	v_mfma_f32_16x16x32_bf16 v[92:95], v[160:163], v[246:249], v[92:95]
	ds_read_b128 v[160:163], v215
	v_mfma_f32_16x16x32_bf16 v[96:99], v[176:179], v[204:207], v[96:99]
	v_mfma_f32_16x16x32_bf16 v[100:103], v[176:179], v[222:225], v[100:103]
	v_mfma_f32_16x16x32_bf16 v[104:107], v[176:179], v[226:229], v[104:107]
	v_mfma_f32_16x16x32_bf16 v[108:111], v[176:179], v[230:233], v[108:111]
	v_mfma_f32_16x16x32_bf16 v[112:115], v[176:179], v[234:237], v[112:115]
	v_mfma_f32_16x16x32_bf16 v[116:119], v[176:179], v[238:241], v[116:119]
	v_mfma_f32_16x16x32_bf16 v[120:123], v[176:179], v[242:245], v[120:123]
	v_mfma_f32_16x16x32_bf16 v[124:127], v[176:179], v[246:249], v[124:127]
	ds_read_b128 v[176:179], v215 offset:2048
	v_mfma_f32_16x16x32_bf16 v[0:3], v[180:183], v[204:207], v[0:3]
	v_mfma_f32_16x16x32_bf16 v[4:7], v[180:183], v[222:225], v[4:7]
	v_mfma_f32_16x16x32_bf16 v[8:11], v[180:183], v[226:229], v[8:11]
	v_mfma_f32_16x16x32_bf16 v[12:15], v[180:183], v[230:233], v[12:15]
	v_mfma_f32_16x16x32_bf16 v[16:19], v[180:183], v[234:237], v[16:19]
	v_mfma_f32_16x16x32_bf16 v[20:23], v[180:183], v[238:241], v[20:23]
	v_mfma_f32_16x16x32_bf16 v[24:27], v[180:183], v[242:245], v[24:27]
	v_mfma_f32_16x16x32_bf16 v[28:31], v[180:183], v[246:249], v[28:31]
	ds_read_b128 v[180:183], v215 offset:4096
	s_waitcnt lgkmcnt(3)
; DI void lds_barrier() { asm volatile("s_waitcnt lgkmcnt(0)\n\ts_barrier" ::: "memory"); }
; #define G_LOAD(RA, RB, KT) { size_t as_ = astep, bs_ = bstep; asm volatile("" : "+s"(as_), "+s"(bs_)); \
;       _Pragma("unroll") for (int i = 0; i < 4; ++i) { RA[i] = *(const u32x4*)(Ag + i * as_ + (KT) * 64); RB[i] = *(const u32x4*)(Bg + i * bs_ + (KT) * 64); } }
; DI void gemm_run(const GemmCfg c, char* smem, float* const g_h, u16* const g_hb, float* const g_out, const int final_out) {
;     ...
;     G_LOAD(ra0, rb0, 0);
;     __syncthreads();
;     G_STORE(ra0, rb0, 0);
;     G_LOAD(ra0, rb0, 1);
;     lds_barrier();
;     int kt = 0;
;     for (; kt + 3 < nk; kt += 2) {
;       K_STEP(0, 1, kt + 2, true, true);
;       lds_barrier();
;       K_STEP(1, 0, kt + 3, true, true);
;       lds_barrier();
;     }
	v_mfma_f32_16x16x32_bf16 v[32:35], v[200:203], v[204:207], v[32:35]
	ds_read_b128 v[204:207], v197
	v_mfma_f32_16x16x32_bf16 v[36:39], v[200:203], v[222:225], v[36:39]
	ds_read_b128 v[222:225], v197 offset:2048
	v_mfma_f32_16x16x32_bf16 v[40:43], v[200:203], v[226:229], v[40:43]
	ds_read_b128 v[226:229], v197 offset:4096
	v_mfma_f32_16x16x32_bf16 v[44:47], v[200:203], v[230:233], v[44:47]
	ds_read_b128 v[230:233], v197 offset:6144
	v_mfma_f32_16x16x32_bf16 v[48:51], v[200:203], v[234:237], v[48:51]
	ds_read_b128 v[234:237], v197 offset:8192
	v_mfma_f32_16x16x32_bf16 v[52:55], v[200:203], v[238:241], v[52:55]
	ds_read_b128 v[238:241], v197 offset:10240
	v_mfma_f32_16x16x32_bf16 v[56:59], v[200:203], v[242:245], v[56:59]
	ds_read_b128 v[242:245], v197 offset:12288
	v_mfma_f32_16x16x32_bf16 v[60:63], v[200:203], v[246:249], v[60:63]
	ds_read_b128 v[246:249], v197 offset:14336
	ds_read_b128 v[200:203], v215 offset:6144
	s_waitcnt lgkmcnt(8)
	v_mfma_f32_16x16x32_bf16 v[64:67], v[160:163], v[204:207], v[64:67]
	s_waitcnt lgkmcnt(7)
	v_mfma_f32_16x16x32_bf16 v[68:71], v[160:163], v[222:225], v[68:71]
	s_waitcnt lgkmcnt(6)
	v_mfma_f32_16x16x32_bf16 v[72:75], v[160:163], v[226:229], v[72:75]
	s_waitcnt lgkmcnt(5)
	v_mfma_f32_16x16x32_bf16 v[76:79], v[160:163], v[230:233], v[76:79]
	s_waitcnt lgkmcnt(4)
	v_mfma_f32_16x16x32_bf16 v[80:83], v[160:163], v[234:237], v[80:83]
	s_waitcnt lgkmcnt(3)
	v_mfma_f32_16x16x32_bf16 v[84:87], v[160:163], v[238:241], v[84:87]
	s_waitcnt lgkmcnt(2)
	v_mfma_f32_16x16x32_bf16 v[88:91], v[160:163], v[242:245], v[88:91]
	s_waitcnt lgkmcnt(1)
	v_mfma_f32_16x16x32_bf16 v[92:95], v[160:163], v[246:249], v[92:95]
	s_waitcnt vmcnt(0) lgkmcnt(0)
	s_barrier
	s_add_u32 m0, s8, 0x0
	ds_read_b128 v[160:163], v194 offset:36864
	v_mfma_f32_16x16x32_bf16 v[96:99], v[176:179], v[204:207], v[96:99]
	global_load_lds_dwordx4 v130, s[4:5]
	v_mfma_f32_16x16x32_bf16 v[100:103], v[176:179], v[222:225], v[100:103]
	s_add_u32 m0, s8, 0x12000
	v_mfma_f32_16x16x32_bf16 v[104:107], v[176:179], v[226:229], v[104:107]
	global_load_lds_dwordx4 v134, s[6:7]
	v_mfma_f32_16x16x32_bf16 v[108:111], v[176:179], v[230:233], v[108:111]
	s_add_u32 m0, s8, 0x400
	v_mfma_f32_16x16x32_bf16 v[112:115], v[176:179], v[234:237], v[112:115]
	global_load_lds_dwordx4 v131, s[4:5]
	v_mfma_f32_16x16x32_bf16 v[116:119], v[176:179], v[238:241], v[116:119]
	s_add_u32 m0, s8, 0x12400
	v_mfma_f32_16x16x32_bf16 v[120:123], v[176:179], v[242:245], v[120:123]
	global_load_lds_dwordx4 v135, s[6:7]
	v_mfma_f32_16x16x32_bf16 v[124:127], v[176:179], v[246:249], v[124:127]
	s_add_u32 m0, s8, 0x800
	ds_read_b128 v[176:179], v194 offset:38912
	v_mfma_f32_16x16x32_bf16 v[0:3], v[180:183], v[204:207], v[0:3]
	global_load_lds_dwordx4 v132, s[4:5]
	v_mfma_f32_16x16x32_bf16 v[4:7], v[180:183], v[222:225], v[4:7]
	s_add_u32 m0, s8, 0x12800
	v_mfma_f32_16x16x32_bf16 v[8:11], v[180:183], v[226:229], v[8:11]
	global_load_lds_dwordx4 v136, s[6:7]
	v_mfma_f32_16x16x32_bf16 v[12:15], v[180:183], v[230:233], v[12:15]
	s_add_u32 m0, s8, 0xc00
	v_mfma_f32_16x16x32_bf16 v[16:19], v[180:183], v[234:237], v[16:19]
	global_load_lds_dwordx4 v133, s[4:5]
	v_mfma_f32_16x16x32_bf16 v[20:23], v[180:183], v[238:241], v[20:23]
	s_add_u32 m0, s8, 0x12c00
	v_mfma_f32_16x16x32_bf16 v[24:27], v[180:183], v[242:245], v[24:27]
	global_load_lds_dwordx4 v137, s[6:7]
	v_mfma_f32_16x16x32_bf16 v[28:31], v[180:183], v[246:249], v[28:31]
	s_add_u32 s4, s4, 0x80
	s_addc_u32 s5, s5, 0
	s_add_u32 s6, s6, 0x80
	s_addc_u32 s7, s7, 0
	ds_read_b128 v[180:183], v194 offset:40960
	v_mfma_f32_16x16x32_bf16 v[32:35], v[200:203], v[204:207], v[32:35]
	ds_read_b128 v[204:207], v195 offset:36864
	v_mfma_f32_16x16x32_bf16 v[36:39], v[200:203], v[222:225], v[36:39]
	ds_read_b128 v[222:225], v195 offset:38912
	v_mfma_f32_16x16x32_bf16 v[40:43], v[200:203], v[226:229], v[40:43]
	ds_read_b128 v[226:229], v195 offset:40960
	v_mfma_f32_16x16x32_bf16 v[44:47], v[200:203], v[230:233], v[44:47]
	ds_read_b128 v[230:233], v195 offset:43008
	v_mfma_f32_16x16x32_bf16 v[48:51], v[200:203], v[234:237], v[48:51]
	ds_read_b128 v[234:237], v195 offset:45056
	v_mfma_f32_16x16x32_bf16 v[52:55], v[200:203], v[238:241], v[52:55]
	ds_read_b128 v[238:241], v195 offset:47104
	v_mfma_f32_16x16x32_bf16 v[56:59], v[200:203], v[242:245], v[56:59]
	ds_read_b128 v[242:245], v195 offset:49152
	v_mfma_f32_16x16x32_bf16 v[60:63], v[200:203], v[246:249], v[60:63]
	ds_read_b128 v[246:249], v195 offset:51200
	ds_read_b128 v[200:203], v194 offset:43008
	s_waitcnt lgkmcnt(8)
	v_mfma_f32_16x16x32_bf16 v[64:67], v[160:163], v[204:207], v[64:67]
	s_waitcnt lgkmcnt(7)
	v_mfma_f32_16x16x32_bf16 v[68:71], v[160:163], v[222:225], v[68:71]
	s_waitcnt lgkmcnt(6)
	v_mfma_f32_16x16x32_bf16 v[72:75], v[160:163], v[226:229], v[72:75]
	s_waitcnt lgkmcnt(5)
	v_mfma_f32_16x16x32_bf16 v[76:79], v[160:163], v[230:233], v[76:79]
	s_waitcnt lgkmcnt(4)
	v_mfma_f32_16x16x32_bf16 v[80:83], v[160:163], v[234:237], v[80:83]
	s_waitcnt lgkmcnt(3)
	v_mfma_f32_16x16x32_bf16 v[84:87], v[160:163], v[238:241], v[84:87]
	s_waitcnt lgkmcnt(2)
	v_mfma_f32_16x16x32_bf16 v[88:91], v[160:163], v[242:245], v[88:91]
	s_waitcnt lgkmcnt(1)
; DI void lds_barrier() { asm volatile("s_waitcnt lgkmcnt(0)\n\ts_barrier" ::: "memory"); }
; #define G_LOAD(RA, RB, KT) { size_t as_ = astep, bs_ = bstep; asm volatile("" : "+s"(as_), "+s"(bs_)); \
;       _Pragma("unroll") for (int i = 0; i < 4; ++i) { RA[i] = *(const u32x4*)(Ag + i * as_ + (KT) * 64); RB[i] = *(const u32x4*)(Bg + i * bs_ + (KT) * 64); } }
; DI void gemm_run(const GemmCfg c, char* smem, float* const g_h, u16* const g_hb, float* const g_out, const int final_out) {
;     ...
;     G_LOAD(ra0, rb0, 0);
;     __syncthreads();
;     G_STORE(ra0, rb0, 0);
;     G_LOAD(ra0, rb0, 1);
;     lds_barrier();
;     int kt = 0;
;     for (; kt + 3 < nk; kt += 2) {
;       K_STEP(0, 1, kt + 2, true, true);
;       lds_barrier();
;       K_STEP(1, 0, kt + 3, true, true);
;       lds_barrier();
;     }
	v_mfma_f32_16x16x32_bf16 v[92:95], v[160:163], v[246:249], v[92:95]
	ds_read_b128 v[160:163], v215 offset:36864
	v_mfma_f32_16x16x32_bf16 v[96:99], v[176:179], v[204:207], v[96:99]
	v_mfma_f32_16x16x32_bf16 v[100:103], v[176:179], v[222:225], v[100:103]
	v_mfma_f32_16x16x32_bf16 v[104:107], v[176:179], v[226:229], v[104:107]
	v_mfma_f32_16x16x32_bf16 v[108:111], v[176:179], v[230:233], v[108:111]
	v_mfma_f32_16x16x32_bf16 v[112:115], v[176:179], v[234:237], v[112:115]
	v_mfma_f32_16x16x32_bf16 v[116:119], v[176:179], v[238:241], v[116:119]
	v_mfma_f32_16x16x32_bf16 v[120:123], v[176:179], v[242:245], v[120:123]
	v_mfma_f32_16x16x32_bf16 v[124:127], v[176:179], v[246:249], v[124:127]
	ds_read_b128 v[176:179], v215 offset:38912
	v_mfma_f32_16x16x32_bf16 v[0:3], v[180:183], v[204:207], v[0:3]
	v_mfma_f32_16x16x32_bf16 v[4:7], v[180:183], v[222:225], v[4:7]
	v_mfma_f32_16x16x32_bf16 v[8:11], v[180:183], v[226:229], v[8:11]
	v_mfma_f32_16x16x32_bf16 v[12:15], v[180:183], v[230:233], v[12:15]
	v_mfma_f32_16x16x32_bf16 v[16:19], v[180:183], v[234:237], v[16:19]
	v_mfma_f32_16x16x32_bf16 v[20:23], v[180:183], v[238:241], v[20:23]
	v_mfma_f32_16x16x32_bf16 v[24:27], v[180:183], v[242:245], v[24:27]
	v_mfma_f32_16x16x32_bf16 v[28:31], v[180:183], v[246:249], v[28:31]
	ds_read_b128 v[180:183], v215 offset:40960
	s_waitcnt lgkmcnt(3)
	v_mfma_f32_16x16x32_bf16 v[32:35], v[200:203], v[204:207], v[32:35]
	ds_read_b128 v[204:207], v197 offset:36864
	v_mfma_f32_16x16x32_bf16 v[36:39], v[200:203], v[222:225], v[36:39]
	ds_read_b128 v[222:225], v197 offset:38912
	v_mfma_f32_16x16x32_bf16 v[40:43], v[200:203], v[226:229], v[40:43]
	ds_read_b128 v[226:229], v197 offset:40960
	v_mfma_f32_16x16x32_bf16 v[44:47], v[200:203], v[230:233], v[44:47]
	ds_read_b128 v[230:233], v197 offset:43008
	v_mfma_f32_16x16x32_bf16 v[48:51], v[200:203], v[234:237], v[48:51]
	ds_read_b128 v[234:237], v197 offset:45056
	v_mfma_f32_16x16x32_bf16 v[52:55], v[200:203], v[238:241], v[52:55]
	ds_read_b128 v[238:241], v197 offset:47104
	v_mfma_f32_16x16x32_bf16 v[56:59], v[200:203], v[242:245], v[56:59]
	ds_read_b128 v[242:245], v197 offset:49152
	v_mfma_f32_16x16x32_bf16 v[60:63], v[200:203], v[246:249], v[60:63]
	ds_read_b128 v[246:249], v197 offset:51200
	ds_read_b128 v[200:203], v215 offset:43008
	s_waitcnt lgkmcnt(8)
	v_mfma_f32_16x16x32_bf16 v[64:67], v[160:163], v[204:207], v[64:67]
	s_waitcnt lgkmcnt(7)
	v_mfma_f32_16x16x32_bf16 v[68:71], v[160:163], v[222:225], v[68:71]
	s_waitcnt lgkmcnt(6)
	v_mfma_f32_16x16x32_bf16 v[72:75], v[160:163], v[226:229], v[72:75]
	s_waitcnt lgkmcnt(5)
	v_mfma_f32_16x16x32_bf16 v[76:79], v[160:163], v[230:233], v[76:79]
	s_waitcnt lgkmcnt(4)
	v_mfma_f32_16x16x32_bf16 v[80:83], v[160:163], v[234:237], v[80:83]
	s_waitcnt lgkmcnt(3)
	v_mfma_f32_16x16x32_bf16 v[84:87], v[160:163], v[238:241], v[84:87]
	s_waitcnt lgkmcnt(2)
	v_mfma_f32_16x16x32_bf16 v[88:91], v[160:163], v[242:245], v[88:91]
	s_waitcnt lgkmcnt(1)
	v_mfma_f32_16x16x32_bf16 v[92:95], v[160:163], v[246:249], v[92:95]
	s_waitcnt vmcnt(0) lgkmcnt(0)
	s_barrier
	s_add_u32 m0, s8, 0x9000
	ds_read_b128 v[160:163], v194
	v_mfma_f32_16x16x32_bf16 v[96:99], v[176:179], v[204:207], v[96:99]
	global_load_lds_dwordx4 v130, s[4:5]
	v_mfma_f32_16x16x32_bf16 v[100:103], v[176:179], v[222:225], v[100:103]
	s_add_u32 m0, s8, 0x1b000
	v_mfma_f32_16x16x32_bf16 v[104:107], v[176:179], v[226:229], v[104:107]
	global_load_lds_dwordx4 v134, s[6:7]
	v_mfma_f32_16x16x32_bf16 v[108:111], v[176:179], v[230:233], v[108:111]
	s_add_u32 m0, s8, 0x9400
	v_mfma_f32_16x16x32_bf16 v[112:115], v[176:179], v[234:237], v[112:115]
	global_load_lds_dwordx4 v131, s[4:5]
	v_mfma_f32_16x16x32_bf16 v[116:119], v[176:179], v[238:241], v[116:119]
	s_add_u32 m0, s8, 0x1b400
	v_mfma_f32_16x16x32_bf16 v[120:123], v[176:179], v[242:245], v[120:123]
	global_load_lds_dwordx4 v135, s[6:7]
	v_mfma_f32_16x16x32_bf16 v[124:127], v[176:179], v[246:249], v[124:127]
	s_add_u32 m0, s8, 0x9800
	ds_read_b128 v[176:179], v194 offset:2048
	v_mfma_f32_16x16x32_bf16 v[0:3], v[180:183], v[204:207], v[0:3]
	global_load_lds_dwordx4 v132, s[4:5]
	v_mfma_f32_16x16x32_bf16 v[4:7], v[180:183], v[222:225], v[4:7]
	s_add_u32 m0, s8, 0x1b800
	v_mfma_f32_16x16x32_bf16 v[8:11], v[180:183], v[226:229], v[8:11]
	global_load_lds_dwordx4 v136, s[6:7]
	v_mfma_f32_16x16x32_bf16 v[12:15], v[180:183], v[230:233], v[12:15]
	s_add_u32 m0, s8, 0x9c00
	v_mfma_f32_16x16x32_bf16 v[16:19], v[180:183], v[234:237], v[16:19]
	global_load_lds_dwordx4 v133, s[4:5]
	v_mfma_f32_16x16x32_bf16 v[20:23], v[180:183], v[238:241], v[20:23]
	s_add_u32 m0, s8, 0x1bc00
	v_mfma_f32_16x16x32_bf16 v[24:27], v[180:183], v[242:245], v[24:27]
	global_load_lds_dwordx4 v137, s[6:7]
	v_mfma_f32_16x16x32_bf16 v[28:31], v[180:183], v[246:249], v[28:31]
	s_add_u32 s4, s4, 0x80
	s_addc_u32 s5, s5, 0
	s_add_u32 s6, s6, 0x80
	s_addc_u32 s7, s7, 0
	ds_read_b128 v[180:183], v194 offset:4096
	v_mfma_f32_16x16x32_bf16 v[32:35], v[200:203], v[204:207], v[32:35]
	ds_read_b128 v[204:207], v195
	v_mfma_f32_16x16x32_bf16 v[36:39], v[200:203], v[222:225], v[36:39]
	ds_read_b128 v[222:225], v195 offset:2048
	v_mfma_f32_16x16x32_bf16 v[40:43], v[200:203], v[226:229], v[40:43]
	ds_read_b128 v[226:229], v195 offset:4096
	v_mfma_f32_16x16x32_bf16 v[44:47], v[200:203], v[230:233], v[44:47]
	ds_read_b128 v[230:233], v195 offset:6144
	v_mfma_f32_16x16x32_bf16 v[48:51], v[200:203], v[234:237], v[48:51]
	ds_read_b128 v[234:237], v195 offset:8192
	v_mfma_f32_16x16x32_bf16 v[52:55], v[200:203], v[238:241], v[52:55]
	ds_read_b128 v[238:241], v195 offset:10240
	v_mfma_f32_16x16x32_bf16 v[56:59], v[200:203], v[242:245], v[56:59]
	ds_read_b128 v[242:245], v195 offset:12288
	v_mfma_f32_16x16x32_bf16 v[60:63], v[200:203], v[246:249], v[60:63]
	ds_read_b128 v[246:249], v195 offset:14336
	ds_read_b128 v[200:203], v194 offset:6144
	s_add_i32 s1, s1, 2
	s_cmp_lt_i32 s1, s0
	s_cbranch_scc1 .Lgemm_kloop_n
; DI void lds_barrier() { asm volatile("s_waitcnt lgkmcnt(0)\n\ts_barrier" ::: "memory"); }
; #define G_LOAD(RA, RB, KT) { size_t as_ = astep, bs_ = bstep; asm volatile("" : "+s"(as_), "+s"(bs_)); \
;       _Pragma("unroll") for (int i = 0; i < 4; ++i) { RA[i] = *(const u32x4*)(Ag + i * as_ + (KT) * 64); RB[i] = *(const u32x4*)(Bg + i * bs_ + (KT) * 64); } }
; DI void gemm_run(const GemmCfg c, char* smem, float* const g_h, u16* const g_hb, float* const g_out, const int final_out) {
;     ...
;     G_LOAD(ra0, rb0, 0);
;     __syncthreads();
;     G_STORE(ra0, rb0, 0);
;     G_LOAD(ra0, rb0, 1);
;     lds_barrier();
;     int kt = 0;
;     for (; kt + 3 < nk; kt += 2) {
;       K_STEP(0, 1, kt + 2, true, true);
;       lds_barrier();
;       K_STEP(1, 0, kt + 3, true, true);
;       lds_barrier();
;     }
;     K_STEP(0, 1, 0, true, false);
;     lds_barrier();
;     K_STEP(1, 0, 0, false, false);
;     lds_barrier();
	s_waitcnt lgkmcnt(8)
	v_mfma_f32_16x16x32_bf16 v[64:67], v[160:163], v[204:207], v[64:67]
	s_waitcnt lgkmcnt(7)
	v_mfma_f32_16x16x32_bf16 v[68:71], v[160:163], v[222:225], v[68:71]
	s_waitcnt lgkmcnt(6)
	v_mfma_f32_16x16x32_bf16 v[72:75], v[160:163], v[226:229], v[72:75]
	s_waitcnt lgkmcnt(5)
	v_mfma_f32_16x16x32_bf16 v[76:79], v[160:163], v[230:233], v[76:79]
	s_waitcnt lgkmcnt(4)
	v_mfma_f32_16x16x32_bf16 v[80:83], v[160:163], v[234:237], v[80:83]
	s_waitcnt lgkmcnt(3)
	v_mfma_f32_16x16x32_bf16 v[84:87], v[160:163], v[238:241], v[84:87]
	s_waitcnt lgkmcnt(2)
	v_mfma_f32_16x16x32_bf16 v[88:91], v[160:163], v[242:245], v[88:91]
	s_waitcnt lgkmcnt(1)
	v_mfma_f32_16x16x32_bf16 v[92:95], v[160:163], v[246:249], v[92:95]
	ds_read_b128 v[160:163], v215
	v_mfma_f32_16x16x32_bf16 v[96:99], v[176:179], v[204:207], v[96:99]
	v_mfma_f32_16x16x32_bf16 v[100:103], v[176:179], v[222:225], v[100:103]
	v_mfma_f32_16x16x32_bf16 v[104:107], v[176:179], v[226:229], v[104:107]
	v_mfma_f32_16x16x32_bf16 v[108:111], v[176:179], v[230:233], v[108:111]
	v_mfma_f32_16x16x32_bf16 v[112:115], v[176:179], v[234:237], v[112:115]
	v_mfma_f32_16x16x32_bf16 v[116:119], v[176:179], v[238:241], v[116:119]
	v_mfma_f32_16x16x32_bf16 v[120:123], v[176:179], v[242:245], v[120:123]
	v_mfma_f32_16x16x32_bf16 v[124:127], v[176:179], v[246:249], v[124:127]
	ds_read_b128 v[176:179], v215 offset:2048
	v_mfma_f32_16x16x32_bf16 v[0:3], v[180:183], v[204:207], v[0:3]
	v_mfma_f32_16x16x32_bf16 v[4:7], v[180:183], v[222:225], v[4:7]
	v_mfma_f32_16x16x32_bf16 v[8:11], v[180:183], v[226:229], v[8:11]
	v_mfma_f32_16x16x32_bf16 v[12:15], v[180:183], v[230:233], v[12:15]
	v_mfma_f32_16x16x32_bf16 v[16:19], v[180:183], v[234:237], v[16:19]
	v_mfma_f32_16x16x32_bf16 v[20:23], v[180:183], v[238:241], v[20:23]
	v_mfma_f32_16x16x32_bf16 v[24:27], v[180:183], v[242:245], v[24:27]
	v_mfma_f32_16x16x32_bf16 v[28:31], v[180:183], v[246:249], v[28:31]
	ds_read_b128 v[180:183], v215 offset:4096
	s_waitcnt lgkmcnt(3)
	v_mfma_f32_16x16x32_bf16 v[32:35], v[200:203], v[204:207], v[32:35]
	ds_read_b128 v[204:207], v197
	v_mfma_f32_16x16x32_bf16 v[36:39], v[200:203], v[222:225], v[36:39]
	ds_read_b128 v[222:225], v197 offset:2048
	v_mfma_f32_16x16x32_bf16 v[40:43], v[200:203], v[226:229], v[40:43]
	ds_read_b128 v[226:229], v197 offset:4096
	v_mfma_f32_16x16x32_bf16 v[44:47], v[200:203], v[230:233], v[44:47]
	ds_read_b128 v[230:233], v197 offset:6144
	v_mfma_f32_16x16x32_bf16 v[48:51], v[200:203], v[234:237], v[48:51]
	ds_read_b128 v[234:237], v197 offset:8192
	v_mfma_f32_16x16x32_bf16 v[52:55], v[200:203], v[238:241], v[52:55]
	ds_read_b128 v[238:241], v197 offset:10240
	v_mfma_f32_16x16x32_bf16 v[56:59], v[200:203], v[242:245], v[56:59]
	ds_read_b128 v[242:245], v197 offset:12288
	v_mfma_f32_16x16x32_bf16 v[60:63], v[200:203], v[246:249], v[60:63]
	ds_read_b128 v[246:249], v197 offset:14336
	ds_read_b128 v[200:203], v215 offset:6144
	s_waitcnt lgkmcnt(8)
	v_mfma_f32_16x16x32_bf16 v[64:67], v[160:163], v[204:207], v[64:67]
	s_waitcnt lgkmcnt(7)
	v_mfma_f32_16x16x32_bf16 v[68:71], v[160:163], v[222:225], v[68:71]
	s_waitcnt lgkmcnt(6)
	v_mfma_f32_16x16x32_bf16 v[72:75], v[160:163], v[226:229], v[72:75]
	s_waitcnt lgkmcnt(5)
	v_mfma_f32_16x16x32_bf16 v[76:79], v[160:163], v[230:233], v[76:79]
	s_waitcnt lgkmcnt(4)
	v_mfma_f32_16x16x32_bf16 v[80:83], v[160:163], v[234:237], v[80:83]
	s_waitcnt lgkmcnt(3)
	v_mfma_f32_16x16x32_bf16 v[84:87], v[160:163], v[238:241], v[84:87]
	s_waitcnt lgkmcnt(2)
	v_mfma_f32_16x16x32_bf16 v[88:91], v[160:163], v[242:245], v[88:91]
	s_waitcnt lgkmcnt(1)
	v_mfma_f32_16x16x32_bf16 v[92:95], v[160:163], v[246:249], v[92:95]
	s_waitcnt vmcnt(0) lgkmcnt(0)
	s_barrier
	ds_read_b128 v[160:163], v194 offset:36864
	v_mfma_f32_16x16x32_bf16 v[96:99], v[176:179], v[204:207], v[96:99]
	v_mfma_f32_16x16x32_bf16 v[100:103], v[176:179], v[222:225], v[100:103]
	v_mfma_f32_16x16x32_bf16 v[104:107], v[176:179], v[226:229], v[104:107]
	v_mfma_f32_16x16x32_bf16 v[108:111], v[176:179], v[230:233], v[108:111]
	v_mfma_f32_16x16x32_bf16 v[112:115], v[176:179], v[234:237], v[112:115]
	v_mfma_f32_16x16x32_bf16 v[116:119], v[176:179], v[238:241], v[116:119]
	v_mfma_f32_16x16x32_bf16 v[120:123], v[176:179], v[242:245], v[120:123]
	v_mfma_f32_16x16x32_bf16 v[124:127], v[176:179], v[246:249], v[124:127]
	ds_read_b128 v[176:179], v194 offset:38912
	v_mfma_f32_16x16x32_bf16 v[0:3], v[180:183], v[204:207], v[0:3]
	v_mfma_f32_16x16x32_bf16 v[4:7], v[180:183], v[222:225], v[4:7]
	v_mfma_f32_16x16x32_bf16 v[8:11], v[180:183], v[226:229], v[8:11]
	v_mfma_f32_16x16x32_bf16 v[12:15], v[180:183], v[230:233], v[12:15]
	v_mfma_f32_16x16x32_bf16 v[16:19], v[180:183], v[234:237], v[16:19]
	v_mfma_f32_16x16x32_bf16 v[20:23], v[180:183], v[238:241], v[20:23]
	v_mfma_f32_16x16x32_bf16 v[24:27], v[180:183], v[242:245], v[24:27]
	v_mfma_f32_16x16x32_bf16 v[28:31], v[180:183], v[246:249], v[28:31]
	ds_read_b128 v[180:183], v194 offset:40960
	v_mfma_f32_16x16x32_bf16 v[32:35], v[200:203], v[204:207], v[32:35]
	ds_read_b128 v[204:207], v195 offset:36864
	v_mfma_f32_16x16x32_bf16 v[36:39], v[200:203], v[222:225], v[36:39]
	ds_read_b128 v[222:225], v195 offset:38912
	v_mfma_f32_16x16x32_bf16 v[40:43], v[200:203], v[226:229], v[40:43]
	ds_read_b128 v[226:229], v195 offset:40960
	v_mfma_f32_16x16x32_bf16 v[44:47], v[200:203], v[230:233], v[44:47]
	ds_read_b128 v[230:233], v195 offset:43008
	v_mfma_f32_16x16x32_bf16 v[48:51], v[200:203], v[234:237], v[48:51]
	ds_read_b128 v[234:237], v195 offset:45056
	v_mfma_f32_16x16x32_bf16 v[52:55], v[200:203], v[238:241], v[52:55]
	ds_read_b128 v[238:241], v195 offset:47104
	v_mfma_f32_16x16x32_bf16 v[56:59], v[200:203], v[242:245], v[56:59]
	ds_read_b128 v[242:245], v195 offset:49152
	v_mfma_f32_16x16x32_bf16 v[60:63], v[200:203], v[246:249], v[60:63]
	ds_read_b128 v[246:249], v195 offset:51200
	ds_read_b128 v[200:203], v194 offset:43008
	s_waitcnt lgkmcnt(8)
; DI float shx(float v, int mask, int lane) { return __int_as_float(__builtin_amdgcn_ds_bpermute((lane ^ mask) << 2, __float_as_int(v))); }
; DI void lds_barrier() { asm volatile("s_waitcnt lgkmcnt(0)\n\ts_barrier" ::: "memory"); }
; #define G_LOAD(RA, RB, KT) { size_t as_ = astep, bs_ = bstep; asm volatile("" : "+s"(as_), "+s"(bs_)); \
;       _Pragma("unroll") for (int i = 0; i < 4; ++i) { RA[i] = *(const u32x4*)(Ag + i * as_ + (KT) * 64); RB[i] = *(const u32x4*)(Bg + i * bs_ + (KT) * 64); } }
; DI void gemm_run(const GemmCfg c, char* smem, float* const g_h, u16* const g_hb, float* const g_out, const int final_out) {
;     ...
;     G_LOAD(ra0, rb0, 0);
;     __syncthreads();
;     G_STORE(ra0, rb0, 0);
;     G_LOAD(ra0, rb0, 1);
;     lds_barrier();
;     int kt = 0;
;     for (; kt + 3 < nk; kt += 2) {
;       K_STEP(0, 1, kt + 2, true, true);
;       lds_barrier();
;       K_STEP(1, 0, kt + 3, true, true);
;       lds_barrier();
;     }
;     K_STEP(0, 1, 0, true, false);
;     lds_barrier();
;     K_STEP(1, 0, 0, false, false);
;     lds_barrier();
;     ...
;     if (c.use_rs) {
; #pragma unroll
;       for (int i = 0; i < 4; ++i) {
;         float s_ = ss[i];
;         s_ += shx(s_, 1, lane); s_ += shx(s_, 2, lane); s_ += shx(s_, 4, lane);
;         if (lch == 0) s_rowss[lrow + 64 * i] = s_;
;       }
;     }
	v_mfma_f32_16x16x32_bf16 v[64:67], v[160:163], v[204:207], v[64:67]
	s_waitcnt lgkmcnt(7)
	v_mfma_f32_16x16x32_bf16 v[68:71], v[160:163], v[222:225], v[68:71]
	s_waitcnt lgkmcnt(6)
	v_mfma_f32_16x16x32_bf16 v[72:75], v[160:163], v[226:229], v[72:75]
	s_waitcnt lgkmcnt(5)
	v_mfma_f32_16x16x32_bf16 v[76:79], v[160:163], v[230:233], v[76:79]
	s_waitcnt lgkmcnt(4)
	v_mfma_f32_16x16x32_bf16 v[80:83], v[160:163], v[234:237], v[80:83]
	s_waitcnt lgkmcnt(3)
	v_mfma_f32_16x16x32_bf16 v[84:87], v[160:163], v[238:241], v[84:87]
	s_waitcnt lgkmcnt(2)
	v_mfma_f32_16x16x32_bf16 v[88:91], v[160:163], v[242:245], v[88:91]
	s_waitcnt lgkmcnt(1)
	v_mfma_f32_16x16x32_bf16 v[92:95], v[160:163], v[246:249], v[92:95]
	ds_read_b128 v[160:163], v215 offset:36864
	v_mfma_f32_16x16x32_bf16 v[96:99], v[176:179], v[204:207], v[96:99]
	v_mfma_f32_16x16x32_bf16 v[100:103], v[176:179], v[222:225], v[100:103]
	v_mfma_f32_16x16x32_bf16 v[104:107], v[176:179], v[226:229], v[104:107]
	v_mfma_f32_16x16x32_bf16 v[108:111], v[176:179], v[230:233], v[108:111]
	v_mfma_f32_16x16x32_bf16 v[112:115], v[176:179], v[234:237], v[112:115]
	v_mfma_f32_16x16x32_bf16 v[116:119], v[176:179], v[238:241], v[116:119]
	v_mfma_f32_16x16x32_bf16 v[120:123], v[176:179], v[242:245], v[120:123]
	v_mfma_f32_16x16x32_bf16 v[124:127], v[176:179], v[246:249], v[124:127]
	ds_read_b128 v[176:179], v215 offset:38912
	v_mfma_f32_16x16x32_bf16 v[0:3], v[180:183], v[204:207], v[0:3]
	v_mfma_f32_16x16x32_bf16 v[4:7], v[180:183], v[222:225], v[4:7]
	v_mfma_f32_16x16x32_bf16 v[8:11], v[180:183], v[226:229], v[8:11]
	v_mfma_f32_16x16x32_bf16 v[12:15], v[180:183], v[230:233], v[12:15]
	v_mfma_f32_16x16x32_bf16 v[16:19], v[180:183], v[234:237], v[16:19]
	v_mfma_f32_16x16x32_bf16 v[20:23], v[180:183], v[238:241], v[20:23]
	v_mfma_f32_16x16x32_bf16 v[24:27], v[180:183], v[242:245], v[24:27]
	v_mfma_f32_16x16x32_bf16 v[28:31], v[180:183], v[246:249], v[28:31]
	ds_read_b128 v[180:183], v215 offset:40960
	s_waitcnt lgkmcnt(3)
	v_mfma_f32_16x16x32_bf16 v[32:35], v[200:203], v[204:207], v[32:35]
	ds_read_b128 v[204:207], v197 offset:36864
	v_mfma_f32_16x16x32_bf16 v[36:39], v[200:203], v[222:225], v[36:39]
	ds_read_b128 v[222:225], v197 offset:38912
	v_mfma_f32_16x16x32_bf16 v[40:43], v[200:203], v[226:229], v[40:43]
	ds_read_b128 v[226:229], v197 offset:40960
	v_mfma_f32_16x16x32_bf16 v[44:47], v[200:203], v[230:233], v[44:47]
	ds_read_b128 v[230:233], v197 offset:43008
	v_mfma_f32_16x16x32_bf16 v[48:51], v[200:203], v[234:237], v[48:51]
	ds_read_b128 v[234:237], v197 offset:45056
	v_mfma_f32_16x16x32_bf16 v[52:55], v[200:203], v[238:241], v[52:55]
	ds_read_b128 v[238:241], v197 offset:47104
	v_mfma_f32_16x16x32_bf16 v[56:59], v[200:203], v[242:245], v[56:59]
	ds_read_b128 v[242:245], v197 offset:49152
	v_mfma_f32_16x16x32_bf16 v[60:63], v[200:203], v[246:249], v[60:63]
	ds_read_b128 v[246:249], v197 offset:51200
	ds_read_b128 v[200:203], v215 offset:43008
	s_waitcnt lgkmcnt(8)
	v_mfma_f32_16x16x32_bf16 v[64:67], v[160:163], v[204:207], v[64:67]
	s_waitcnt lgkmcnt(7)
	v_mfma_f32_16x16x32_bf16 v[68:71], v[160:163], v[222:225], v[68:71]
	s_waitcnt lgkmcnt(6)
	v_mfma_f32_16x16x32_bf16 v[72:75], v[160:163], v[226:229], v[72:75]
	s_waitcnt lgkmcnt(5)
	v_mfma_f32_16x16x32_bf16 v[76:79], v[160:163], v[230:233], v[76:79]
	s_waitcnt lgkmcnt(4)
	v_mfma_f32_16x16x32_bf16 v[80:83], v[160:163], v[234:237], v[80:83]
	s_waitcnt lgkmcnt(3)
	v_mfma_f32_16x16x32_bf16 v[84:87], v[160:163], v[238:241], v[84:87]
	s_waitcnt lgkmcnt(2)
	v_mfma_f32_16x16x32_bf16 v[88:91], v[160:163], v[242:245], v[88:91]
	s_waitcnt lgkmcnt(1)
	v_mfma_f32_16x16x32_bf16 v[92:95], v[160:163], v[246:249], v[92:95]
	v_mfma_f32_16x16x32_bf16 v[96:99], v[176:179], v[204:207], v[96:99]
	v_mfma_f32_16x16x32_bf16 v[100:103], v[176:179], v[222:225], v[100:103]
	v_mfma_f32_16x16x32_bf16 v[104:107], v[176:179], v[226:229], v[104:107]
	v_mfma_f32_16x16x32_bf16 v[108:111], v[176:179], v[230:233], v[108:111]
	v_mfma_f32_16x16x32_bf16 v[112:115], v[176:179], v[234:237], v[112:115]
	v_mfma_f32_16x16x32_bf16 v[116:119], v[176:179], v[238:241], v[116:119]
	v_mfma_f32_16x16x32_bf16 v[120:123], v[176:179], v[242:245], v[120:123]
	v_mfma_f32_16x16x32_bf16 v[124:127], v[176:179], v[246:249], v[124:127]
	v_mfma_f32_16x16x32_bf16 v[0:3], v[180:183], v[204:207], v[0:3]
	v_mfma_f32_16x16x32_bf16 v[4:7], v[180:183], v[222:225], v[4:7]
	v_mfma_f32_16x16x32_bf16 v[8:11], v[180:183], v[226:229], v[8:11]
	v_mfma_f32_16x16x32_bf16 v[12:15], v[180:183], v[230:233], v[12:15]
	v_mfma_f32_16x16x32_bf16 v[16:19], v[180:183], v[234:237], v[16:19]
	v_mfma_f32_16x16x32_bf16 v[20:23], v[180:183], v[238:241], v[20:23]
	v_mfma_f32_16x16x32_bf16 v[24:27], v[180:183], v[242:245], v[24:27]
	v_mfma_f32_16x16x32_bf16 v[28:31], v[180:183], v[246:249], v[28:31]
	s_waitcnt lgkmcnt(0)
	v_mfma_f32_16x16x32_bf16 v[32:35], v[200:203], v[204:207], v[32:35]
	v_mfma_f32_16x16x32_bf16 v[36:39], v[200:203], v[222:225], v[36:39]
	v_mfma_f32_16x16x32_bf16 v[40:43], v[200:203], v[226:229], v[40:43]
	v_mfma_f32_16x16x32_bf16 v[44:47], v[200:203], v[230:233], v[44:47]
	v_mfma_f32_16x16x32_bf16 v[48:51], v[200:203], v[234:237], v[48:51]
	v_mfma_f32_16x16x32_bf16 v[52:55], v[200:203], v[238:241], v[52:55]
	v_mfma_f32_16x16x32_bf16 v[56:59], v[200:203], v[242:245], v[56:59]
	v_mfma_f32_16x16x32_bf16 v[60:63], v[200:203], v[246:249], v[60:63]
.Lgemm_kdone:
	s_waitcnt lgkmcnt(0)
	s_barrier
	s_lshl_b32 s0, s49, 8
	v_cndmask_b32_e64 v144, 0, 1, s[88:89]
	v_cmp_ne_u32_e64 s[42:43], 1, v144
	s_cmp_lg_u32 s9, 0
	s_cbranch_scc0 .LBB0_124
	v_lshlrev_b32_e32 v128, 2, v185
	v_xor_b32_e32 v129, 64, v128
	v_xor_b32_e32 v130, 0x80, v128
	ds_bpermute_b32 v131, v129, v199
	ds_bpermute_b32 v132, v129, v198
	ds_bpermute_b32 v133, v129, v171
	ds_bpermute_b32 v134, v129, v164
	s_waitcnt lgkmcnt(0)
	v_add_f32_e32 v199, v199, v131
	v_add_f32_e32 v198, v198, v132
	v_add_f32_e32 v171, v171, v133
	v_add_f32_e32 v164, v164, v134
	ds_bpermute_b32 v131, v130, v199
	ds_bpermute_b32 v132, v130, v198
	ds_bpermute_b32 v133, v130, v171
	ds_bpermute_b32 v134, v130, v164
	s_waitcnt lgkmcnt(0)
	v_add_f32_e32 v199, v199, v131
	v_add_f32_e32 v198, v198, v132
	v_add_f32_e32 v171, v171, v133
	v_add_f32_e32 v164, v164, v134
	s_lshl_b32 s8, s86, 2
	s_add_i32 s8, s8, 0x24000
	v_cmp_gt_u32_e32 vcc, 16, v185
	v_add_u32_e32 v128, s8, v128
	s_nop 1
	s_and_saveexec_b64 s[4:5], vcc
	ds_write_b32 v128, v199
	ds_write_b32 v128, v198 offset:64
	ds_write_b32 v128, v171 offset:128
	ds_write_b32 v128, v164 offset:192
	s_or_b64 exec, exec, s[4:5]
